# GEMM block opening: merged vmcnt+lgkmcnt wait before the barrier and dropped the redundant lgkmcnt(0) after it (20 blocks)
# baseline (speedup 1.0000x reference)
.LBB0_177:
	ds_read_b128 v[128:131], v171
	ds_read_b128 v[132:135], v171 offset:1024
	ds_read_b128 v[136:139], v171 offset:2048
	ds_read_b128 v[160:163], v171 offset:3072
	ds_read_b128 v[164:167], v172
	ds_read_b128 v[174:177], v172 offset:1024
	ds_read_b128 v[178:181], v172 offset:2048
	ds_read_b128 v[182:185], v172 offset:3072
	s_add_u32 s52, s44, 0xfffc0080
	s_addc_u32 s53, s45, -1
	s_cmp_eq_u32 s84, 12
	s_cselect_b32 s57, s7, s53
	s_cselect_b32 s56, s8, s52
	s_cselect_b32 s53, s27, s83
	s_cselect_b32 s52, s29, s43
	v_lshl_add_u64 v[198:199], s[44:45], 0, v[152:153]
	s_add_i32 m0, s33, 0xc000
	ds_read_b128 v[186:189], v173
	ds_read_b128 v[190:193], v173 offset:1024
	ds_read_b128 v[194:197], v173 offset:2048
	ds_read_b128 v[202:205], v173 offset:3072
	ds_read_b128 v[206:209], v173 offset:4096
	ds_read_b128 v[210:213], v173 offset:5120
	ds_read_b128 v[214:217], v173 offset:6144
	ds_read_b128 v[218:221], v173 offset:7168
	global_load_lds_dwordx4 v[198:199], off
	s_add_i32 m0, s33, 0xe000
	v_lshl_add_u64 v[198:199], s[44:45], 0, v[154:155]
	global_load_lds_dwordx4 v[198:199], off
	s_waitcnt vmcnt(8) lgkmcnt(0)
	s_barrier
	v_mfma_f32_16x16x32_bf16 v[124:127], v[128:131], v[186:189], v[124:127]
	v_mfma_f32_16x16x32_bf16 v[120:123], v[136:139], v[186:189], v[120:123]
	v_mfma_f32_16x16x32_bf16 v[112:115], v[128:131], v[194:197], v[112:115]
	v_mfma_f32_16x16x32_bf16 v[104:107], v[136:139], v[194:197], v[104:107]
	v_mfma_f32_16x16x32_bf16 v[100:103], v[128:131], v[206:209], v[100:103]
	v_mfma_f32_16x16x32_bf16 v[92:95], v[136:139], v[206:209], v[92:95]
	v_mfma_f32_16x16x32_bf16 v[84:87], v[128:131], v[214:217], v[84:87]
	v_mfma_f32_16x16x32_bf16 v[76:79], v[136:139], v[214:217], v[76:79]
	v_mfma_f32_16x16x32_bf16 v[124:127], v[132:135], v[190:193], v[124:127]
	v_mfma_f32_16x16x32_bf16 v[120:123], v[160:163], v[190:193], v[120:123]
	v_mfma_f32_16x16x32_bf16 v[112:115], v[132:135], v[202:205], v[112:115]
	v_mfma_f32_16x16x32_bf16 v[104:107], v[160:163], v[202:205], v[104:107]
	v_mfma_f32_16x16x32_bf16 v[100:103], v[132:135], v[210:213], v[100:103]
	v_mfma_f32_16x16x32_bf16 v[92:95], v[160:163], v[210:213], v[92:95]
	v_mfma_f32_16x16x32_bf16 v[84:87], v[132:135], v[218:221], v[84:87]
	v_mfma_f32_16x16x32_bf16 v[76:79], v[160:163], v[218:221], v[76:79]
	v_mfma_f32_16x16x32_bf16 v[116:119], v[164:167], v[186:189], v[116:119]
	v_mfma_f32_16x16x32_bf16 v[108:111], v[178:181], v[186:189], v[108:111]
	v_mfma_f32_16x16x32_bf16 v[96:99], v[164:167], v[194:197], v[96:99]
	v_mfma_f32_16x16x32_bf16 v[88:91], v[178:181], v[194:197], v[88:91]
	v_mfma_f32_16x16x32_bf16 v[80:83], v[164:167], v[206:209], v[80:83]
	v_mfma_f32_16x16x32_bf16 v[72:75], v[178:181], v[206:209], v[72:75]
	v_mfma_f32_16x16x32_bf16 v[68:71], v[164:167], v[214:217], v[68:71]
	v_mfma_f32_16x16x32_bf16 v[64:67], v[178:181], v[214:217], v[64:67]
	v_mfma_f32_16x16x32_bf16 v[116:119], v[174:177], v[190:193], v[116:119]
	v_mfma_f32_16x16x32_bf16 v[108:111], v[182:185], v[190:193], v[108:111]
	v_mfma_f32_16x16x32_bf16 v[96:99], v[174:177], v[202:205], v[96:99]
	v_mfma_f32_16x16x32_bf16 v[88:91], v[182:185], v[202:205], v[88:91]
	v_mfma_f32_16x16x32_bf16 v[80:83], v[174:177], v[210:213], v[80:83]
	v_mfma_f32_16x16x32_bf16 v[72:75], v[182:185], v[210:213], v[72:75]
	v_mfma_f32_16x16x32_bf16 v[68:71], v[174:177], v[218:221], v[68:71]
	v_mfma_f32_16x16x32_bf16 v[64:67], v[182:185], v[218:221], v[64:67]
	s_barrier
	s_add_i32 s85, s80, s3
	v_lshl_add_u64 v[198:199], s[52:53], 0, v[142:143]
	s_mov_b32 m0, s85
	ds_read_b128 v[186:189], v173 offset:16384
	ds_read_b128 v[190:193], v173 offset:17408
	ds_read_b128 v[194:197], v173 offset:18432
	ds_read_b128 v[202:205], v173 offset:19456
	ds_read_b128 v[206:209], v173 offset:20480
	ds_read_b128 v[210:213], v173 offset:21504
	ds_read_b128 v[214:217], v173 offset:22528
	ds_read_b128 v[218:221], v173 offset:23552
	global_load_lds_dwordx4 v[198:199], off
	s_add_i32 m0, s85, 0x2000
	s_add_u32 s86, s52, 0x40000
	v_lshl_add_u64 v[200:201], s[52:53], 0, v[146:147]
	s_addc_u32 s87, s53, 0
	s_add_i32 s85, s81, s3
	global_load_lds_dwordx4 v[200:201], off
	v_lshl_add_u64 v[222:223], s[86:87], 0, v[142:143]
	s_mov_b32 m0, s85
	v_lshl_add_u64 v[224:225], s[56:57], 0, v[144:145]
	global_load_lds_dwordx4 v[222:223], off
	s_add_i32 m0, s85, 0x2000
	v_lshl_add_u64 v[222:223], s[86:87], 0, v[146:147]
	global_load_lds_dwordx4 v[222:223], off
	s_mov_b32 m0, s33
	v_lshl_add_u64 v[222:223], s[56:57], 0, v[140:141]
	global_load_lds_dwordx4 v[222:223], off
	s_mov_b32 m0, s62
	s_nop 0
	global_load_lds_dwordx4 v[224:225], off
	s_waitcnt vmcnt(8) lgkmcnt(0)
	s_barrier
	v_mfma_f32_16x16x32_bf16 v[60:63], v[128:131], v[186:189], v[60:63]
	v_mfma_f32_16x16x32_bf16 v[56:59], v[136:139], v[186:189], v[56:59]
	v_mfma_f32_16x16x32_bf16 v[52:55], v[128:131], v[194:197], v[52:55]
	v_mfma_f32_16x16x32_bf16 v[44:47], v[136:139], v[194:197], v[44:47]
	v_mfma_f32_16x16x32_bf16 v[36:39], v[128:131], v[206:209], v[36:39]
	v_mfma_f32_16x16x32_bf16 v[28:31], v[136:139], v[206:209], v[28:31]
	v_mfma_f32_16x16x32_bf16 v[20:23], v[128:131], v[214:217], v[20:23]
	v_mfma_f32_16x16x32_bf16 v[12:15], v[136:139], v[214:217], v[12:15]
	v_mfma_f32_16x16x32_bf16 v[60:63], v[132:135], v[190:193], v[60:63]
	v_mfma_f32_16x16x32_bf16 v[56:59], v[160:163], v[190:193], v[56:59]
	v_mfma_f32_16x16x32_bf16 v[52:55], v[132:135], v[202:205], v[52:55]
	v_mfma_f32_16x16x32_bf16 v[44:47], v[160:163], v[202:205], v[44:47]
	v_mfma_f32_16x16x32_bf16 v[36:39], v[132:135], v[210:213], v[36:39]
	v_mfma_f32_16x16x32_bf16 v[28:31], v[160:163], v[210:213], v[28:31]
	v_mfma_f32_16x16x32_bf16 v[20:23], v[132:135], v[218:221], v[20:23]
	v_mfma_f32_16x16x32_bf16 v[12:15], v[160:163], v[218:221], v[12:15]
	v_mfma_f32_16x16x32_bf16 v[48:51], v[164:167], v[186:189], v[48:51]
	v_mfma_f32_16x16x32_bf16 v[40:43], v[178:181], v[186:189], v[40:43]
	v_mfma_f32_16x16x32_bf16 v[32:35], v[164:167], v[194:197], v[32:35]
	v_mfma_f32_16x16x32_bf16 v[24:27], v[178:181], v[194:197], v[24:27]
	v_mfma_f32_16x16x32_bf16 v[16:19], v[164:167], v[206:209], v[16:19]
	v_mfma_f32_16x16x32_bf16 v[8:11], v[178:181], v[206:209], v[8:11]
	v_mfma_f32_16x16x32_bf16 v[4:7], v[164:167], v[214:217], v[4:7]
	v_mfma_f32_16x16x32_bf16 v[0:3], v[178:181], v[214:217], v[0:3]
	v_mfma_f32_16x16x32_bf16 v[48:51], v[174:177], v[190:193], v[48:51]
	v_mfma_f32_16x16x32_bf16 v[40:43], v[182:185], v[190:193], v[40:43]
	v_mfma_f32_16x16x32_bf16 v[32:35], v[174:177], v[202:205], v[32:35]
	v_mfma_f32_16x16x32_bf16 v[24:27], v[182:185], v[202:205], v[24:27]
	v_mfma_f32_16x16x32_bf16 v[16:19], v[174:177], v[210:213], v[16:19]
	v_mfma_f32_16x16x32_bf16 v[8:11], v[182:185], v[210:213], v[8:11]
	v_mfma_f32_16x16x32_bf16 v[4:7], v[174:177], v[218:221], v[4:7]
	v_mfma_f32_16x16x32_bf16 v[0:3], v[182:185], v[218:221], v[0:3]
	s_barrier
	s_add_i32 s85, 0, 0x18000
	v_add_u32_e32 v148, s85, v169
	s_add_i32 s86, 0, 0x1c000
	ds_read_b128 v[128:131], v148
	ds_read_b128 v[132:135], v148 offset:1024
	ds_read_b128 v[136:139], v148 offset:2048
	ds_read_b128 v[160:163], v148 offset:3072
	v_add_u32_e32 v148, s86, v169
	ds_read_b128 v[164:167], v148
	ds_read_b128 v[174:177], v148 offset:1024
	ds_read_b128 v[178:181], v148 offset:2048
	ds_read_b128 v[182:185], v148 offset:3072
	s_add_u32 s56, s56, 0x40000
	s_addc_u32 s57, s57, 0
	s_mov_b32 m0, s63
	v_lshl_add_u64 v[226:227], s[56:57], 0, v[140:141]
	ds_read_b128 v[186:189], v173 offset:32768
	ds_read_b128 v[190:193], v173 offset:33792
	ds_read_b128 v[194:197], v173 offset:34816
	ds_read_b128 v[202:205], v173 offset:35840
	ds_read_b128 v[206:209], v173 offset:36864
	ds_read_b128 v[210:213], v173 offset:37888
	ds_read_b128 v[214:217], v173 offset:38912
	ds_read_b128 v[218:221], v173 offset:39936
	global_load_lds_dwordx4 v[226:227], off
	s_mov_b32 m0, s64
	v_lshl_add_u64 v[226:227], s[56:57], 0, v[144:145]
	global_load_lds_dwordx4 v[226:227], off
	s_waitcnt vmcnt(8) lgkmcnt(0)
	s_barrier
	v_mfma_f32_16x16x32_bf16 v[124:127], v[128:131], v[186:189], v[124:127]
	v_mfma_f32_16x16x32_bf16 v[120:123], v[136:139], v[186:189], v[120:123]
	v_mfma_f32_16x16x32_bf16 v[112:115], v[128:131], v[194:197], v[112:115]
	v_mfma_f32_16x16x32_bf16 v[104:107], v[136:139], v[194:197], v[104:107]
	v_mfma_f32_16x16x32_bf16 v[100:103], v[128:131], v[206:209], v[100:103]
	v_mfma_f32_16x16x32_bf16 v[92:95], v[136:139], v[206:209], v[92:95]
	v_mfma_f32_16x16x32_bf16 v[84:87], v[128:131], v[214:217], v[84:87]
	v_mfma_f32_16x16x32_bf16 v[76:79], v[136:139], v[214:217], v[76:79]
	v_mfma_f32_16x16x32_bf16 v[124:127], v[132:135], v[190:193], v[124:127]
	v_mfma_f32_16x16x32_bf16 v[120:123], v[160:163], v[190:193], v[120:123]
	v_mfma_f32_16x16x32_bf16 v[112:115], v[132:135], v[202:205], v[112:115]
	v_mfma_f32_16x16x32_bf16 v[104:107], v[160:163], v[202:205], v[104:107]
	v_mfma_f32_16x16x32_bf16 v[100:103], v[132:135], v[210:213], v[100:103]
	v_mfma_f32_16x16x32_bf16 v[92:95], v[160:163], v[210:213], v[92:95]
	v_mfma_f32_16x16x32_bf16 v[84:87], v[132:135], v[218:221], v[84:87]
	v_mfma_f32_16x16x32_bf16 v[76:79], v[160:163], v[218:221], v[76:79]
	v_mfma_f32_16x16x32_bf16 v[116:119], v[164:167], v[186:189], v[116:119]
	v_mfma_f32_16x16x32_bf16 v[108:111], v[178:181], v[186:189], v[108:111]
	v_mfma_f32_16x16x32_bf16 v[96:99], v[164:167], v[194:197], v[96:99]
	v_mfma_f32_16x16x32_bf16 v[88:91], v[178:181], v[194:197], v[88:91]
	v_mfma_f32_16x16x32_bf16 v[80:83], v[164:167], v[206:209], v[80:83]
	v_mfma_f32_16x16x32_bf16 v[72:75], v[178:181], v[206:209], v[72:75]
	v_mfma_f32_16x16x32_bf16 v[68:71], v[164:167], v[214:217], v[68:71]
	v_mfma_f32_16x16x32_bf16 v[64:67], v[178:181], v[214:217], v[64:67]
	v_mfma_f32_16x16x32_bf16 v[116:119], v[174:177], v[190:193], v[116:119]
	v_mfma_f32_16x16x32_bf16 v[108:111], v[182:185], v[190:193], v[108:111]
	v_mfma_f32_16x16x32_bf16 v[96:99], v[174:177], v[202:205], v[96:99]
	v_mfma_f32_16x16x32_bf16 v[88:91], v[182:185], v[202:205], v[88:91]
	v_mfma_f32_16x16x32_bf16 v[80:83], v[174:177], v[210:213], v[80:83]
	v_mfma_f32_16x16x32_bf16 v[72:75], v[182:185], v[210:213], v[72:75]
	v_mfma_f32_16x16x32_bf16 v[68:71], v[174:177], v[218:221], v[68:71]
	v_mfma_f32_16x16x32_bf16 v[64:67], v[182:185], v[218:221], v[64:67]
	s_barrier
	s_add_i32 s56, s85, s3
	v_lshl_add_u64 v[198:199], v[198:199], 0, s[16:17]
	s_mov_b32 m0, s56
	ds_read_b128 v[186:189], v173 offset:49152
	ds_read_b128 v[190:193], v173 offset:50176
	ds_read_b128 v[194:197], v173 offset:51200
	ds_read_b128 v[202:205], v173 offset:52224
	ds_read_b128 v[206:209], v173 offset:53248
	ds_read_b128 v[210:213], v173 offset:54272
	ds_read_b128 v[214:217], v173 offset:55296
	ds_read_b128 v[218:221], v173 offset:56320
	global_load_lds_dwordx4 v[198:199], off
	s_add_i32 m0, s56, 0x2000
	s_add_u32 s52, s52, 0x40080
	v_lshl_add_u64 v[198:199], v[200:201], 0, s[16:17]
	s_addc_u32 s53, s53, 0
	s_add_i32 s56, s86, s3
	global_load_lds_dwordx4 v[198:199], off
	s_mov_b32 m0, s56
	v_lshl_add_u64 v[198:199], s[52:53], 0, v[142:143]
	global_load_lds_dwordx4 v[198:199], off
	s_add_i32 m0, s56, 0x2000
	v_lshl_add_u64 v[198:199], s[52:53], 0, v[146:147]
	global_load_lds_dwordx4 v[198:199], off
	s_mov_b32 m0, s69
	v_lshl_add_u64 v[198:199], v[222:223], 0, s[16:17]
	global_load_lds_dwordx4 v[198:199], off
	s_mov_b32 m0, s72
	v_lshl_add_u64 v[198:199], v[224:225], 0, s[16:17]
	global_load_lds_dwordx4 v[198:199], off
	s_waitcnt vmcnt(8) lgkmcnt(0)
	s_barrier
	v_mfma_f32_16x16x32_bf16 v[60:63], v[128:131], v[186:189], v[60:63]
	v_mfma_f32_16x16x32_bf16 v[56:59], v[136:139], v[186:189], v[56:59]
	v_mfma_f32_16x16x32_bf16 v[52:55], v[128:131], v[194:197], v[52:55]
	v_mfma_f32_16x16x32_bf16 v[44:47], v[136:139], v[194:197], v[44:47]
	v_mfma_f32_16x16x32_bf16 v[36:39], v[128:131], v[206:209], v[36:39]
	v_mfma_f32_16x16x32_bf16 v[28:31], v[136:139], v[206:209], v[28:31]
	v_mfma_f32_16x16x32_bf16 v[20:23], v[128:131], v[214:217], v[20:23]
	v_mfma_f32_16x16x32_bf16 v[12:15], v[136:139], v[214:217], v[12:15]
	v_mfma_f32_16x16x32_bf16 v[60:63], v[132:135], v[190:193], v[60:63]
	v_mfma_f32_16x16x32_bf16 v[56:59], v[160:163], v[190:193], v[56:59]
	v_mfma_f32_16x16x32_bf16 v[52:55], v[132:135], v[202:205], v[52:55]
	v_mfma_f32_16x16x32_bf16 v[44:47], v[160:163], v[202:205], v[44:47]
	v_mfma_f32_16x16x32_bf16 v[36:39], v[132:135], v[210:213], v[36:39]
	v_mfma_f32_16x16x32_bf16 v[28:31], v[160:163], v[210:213], v[28:31]
	v_mfma_f32_16x16x32_bf16 v[20:23], v[132:135], v[218:221], v[20:23]
	v_mfma_f32_16x16x32_bf16 v[12:15], v[160:163], v[218:221], v[12:15]
	v_mfma_f32_16x16x32_bf16 v[48:51], v[164:167], v[186:189], v[48:51]
	v_mfma_f32_16x16x32_bf16 v[40:43], v[178:181], v[186:189], v[40:43]
	v_mfma_f32_16x16x32_bf16 v[32:35], v[164:167], v[194:197], v[32:35]
	v_mfma_f32_16x16x32_bf16 v[24:27], v[178:181], v[194:197], v[24:27]
	v_mfma_f32_16x16x32_bf16 v[16:19], v[164:167], v[206:209], v[16:19]
	v_mfma_f32_16x16x32_bf16 v[8:11], v[178:181], v[206:209], v[8:11]
	v_mfma_f32_16x16x32_bf16 v[4:7], v[164:167], v[214:217], v[4:7]
	v_mfma_f32_16x16x32_bf16 v[0:3], v[178:181], v[214:217], v[0:3]
	v_mfma_f32_16x16x32_bf16 v[48:51], v[174:177], v[190:193], v[48:51]
	v_mfma_f32_16x16x32_bf16 v[40:43], v[182:185], v[190:193], v[40:43]
	v_mfma_f32_16x16x32_bf16 v[32:35], v[174:177], v[202:205], v[32:35]
	v_mfma_f32_16x16x32_bf16 v[24:27], v[182:185], v[202:205], v[24:27]
	v_mfma_f32_16x16x32_bf16 v[16:19], v[174:177], v[210:213], v[16:19]
	v_mfma_f32_16x16x32_bf16 v[8:11], v[182:185], v[210:213], v[8:11]
	v_mfma_f32_16x16x32_bf16 v[4:7], v[174:177], v[218:221], v[4:7]
	v_mfma_f32_16x16x32_bf16 v[0:3], v[182:185], v[218:221], v[0:3]
	s_barrier
	s_add_i32 s84, s84, 2
	s_add_u32 s44, s44, 0x100
	s_addc_u32 s45, s45, 0
	s_add_u32 s43, s43, 0x100
	s_addc_u32 s83, s83, 0
	s_cmp_gt_u32 s84, 13
	s_cbranch_scc0 .LBB0_177
	s_and_b64 vcc, exec, s[18:19]
	s_cbranch_vccz .LBB0_180
	s_barrier

.LBB0_497:
	s_waitcnt lgkmcnt(0)
	ds_read_b128 v[0:3], v147
	ds_read_b128 v[4:7], v147 offset:1024
	ds_read_b128 v[8:11], v147 offset:2048
	ds_read_b128 v[12:15], v147 offset:3072
	ds_read_b128 v[16:19], v148
	ds_read_b128 v[20:23], v148 offset:1024
	ds_read_b128 v[24:27], v148 offset:2048
	ds_read_b128 v[28:31], v148 offset:3072
	s_ashr_i32 s49, s48, 31
	s_lshl_b64 s[50:51], s[48:49], 17
	s_add_u32 s50, s68, s50
	s_addc_u32 s51, s69, s51
	s_and_b64 s[52:53], s[8:9], exec
	s_cselect_b32 s65, s51, s59
	s_cselect_b32 s64, s50, s58
	s_ashr_i32 s45, s44, 31
	s_lshl_b64 s[52:53], s[44:45], 17
	s_add_u32 s52, s72, s52
	s_addc_u32 s53, s73, s53
	s_and_b64 s[62:63], s[8:9], exec
	s_cselect_b32 s63, s53, s61
	s_cselect_b32 s62, s52, s60
	s_add_u32 s92, s58, 0x10080
	s_addc_u32 s93, s59, 0
	s_add_i32 s94, s81, 0xc000
	v_lshl_add_u64 v[64:65], s[92:93], 0, v[128:129]
	s_mov_b32 m0, s94
	s_add_i32 s45, s81, 0xe000
	ds_read_b128 v[32:35], v149
	ds_read_b128 v[36:39], v149 offset:1024
	ds_read_b128 v[40:43], v149 offset:2048
	ds_read_b128 v[44:47], v149 offset:3072
	ds_read_b128 v[48:51], v149 offset:4096
	ds_read_b128 v[52:55], v149 offset:5120
	ds_read_b128 v[56:59], v149 offset:6144
	ds_read_b128 v[60:63], v149 offset:7168
	global_load_lds_dwordx4 v[64:65], off
	s_mov_b32 m0, s45
	v_lshl_add_u64 v[64:65], s[92:93], 0, v[132:133]
	global_load_lds_dwordx4 v[64:65], off
	s_waitcnt vmcnt(8) lgkmcnt(0)
	s_barrier
	v_mfma_f32_16x16x32_bf16 v[64:67], v[0:3], v[32:35], 0
	v_mfma_f32_16x16x32_bf16 v[68:71], v[8:11], v[32:35], 0
	v_mfma_f32_16x16x32_bf16 v[72:75], v[0:3], v[40:43], 0
	v_mfma_f32_16x16x32_bf16 v[76:79], v[8:11], v[40:43], 0
	v_mfma_f32_16x16x32_bf16 v[80:83], v[0:3], v[48:51], 0
	v_mfma_f32_16x16x32_bf16 v[84:87], v[8:11], v[48:51], 0
	v_mfma_f32_16x16x32_bf16 v[88:91], v[0:3], v[56:59], 0
	v_mfma_f32_16x16x32_bf16 v[92:95], v[8:11], v[56:59], 0
	v_mfma_f32_16x16x32_bf16 v[64:67], v[4:7], v[36:39], v[64:67]
	v_mfma_f32_16x16x32_bf16 v[68:71], v[12:15], v[36:39], v[68:71]
	v_mfma_f32_16x16x32_bf16 v[72:75], v[4:7], v[44:47], v[72:75]
	v_mfma_f32_16x16x32_bf16 v[76:79], v[12:15], v[44:47], v[76:79]
	v_mfma_f32_16x16x32_bf16 v[80:83], v[4:7], v[52:55], v[80:83]
	v_mfma_f32_16x16x32_bf16 v[84:87], v[12:15], v[52:55], v[84:87]
	v_mfma_f32_16x16x32_bf16 v[88:91], v[4:7], v[60:63], v[88:91]
	v_mfma_f32_16x16x32_bf16 v[92:95], v[12:15], v[60:63], v[92:95]
	v_mfma_f32_16x16x32_bf16 v[96:99], v[16:19], v[32:35], 0
	v_mfma_f32_16x16x32_bf16 v[32:35], v[24:27], v[32:35], 0
	v_mfma_f32_16x16x32_bf16 v[96:99], v[20:23], v[36:39], v[96:99]
	v_mfma_f32_16x16x32_bf16 v[32:35], v[28:31], v[36:39], v[32:35]
	v_mfma_f32_16x16x32_bf16 v[36:39], v[16:19], v[40:43], 0
	v_mfma_f32_16x16x32_bf16 v[40:43], v[24:27], v[40:43], 0
	v_mfma_f32_16x16x32_bf16 v[36:39], v[20:23], v[44:47], v[36:39]
	v_mfma_f32_16x16x32_bf16 v[40:43], v[28:31], v[44:47], v[40:43]
	v_mfma_f32_16x16x32_bf16 v[44:47], v[16:19], v[48:51], 0
	v_mfma_f32_16x16x32_bf16 v[48:51], v[24:27], v[48:51], 0
	v_mfma_f32_16x16x32_bf16 v[44:47], v[20:23], v[52:55], v[44:47]
	v_mfma_f32_16x16x32_bf16 v[48:51], v[28:31], v[52:55], v[48:51]
	v_mfma_f32_16x16x32_bf16 v[52:55], v[16:19], v[56:59], 0
	v_mfma_f32_16x16x32_bf16 v[56:59], v[24:27], v[56:59], 0
	v_mfma_f32_16x16x32_bf16 v[52:55], v[20:23], v[60:63], v[52:55]
	v_mfma_f32_16x16x32_bf16 v[56:59], v[28:31], v[60:63], v[56:59]
	s_barrier
	s_add_i32 s92, s88, s80
	v_lshl_add_u64 v[212:213], s[60:61], 0, v[130:131]
	s_add_i32 s49, s92, 0x2000
	v_lshl_add_u64 v[140:141], v[212:213], 0, s[38:39]
	s_mov_b32 m0, s92
	v_lshl_add_u64 v[214:215], s[60:61], 0, v[134:135]
	s_add_u32 s96, s60, 0x10100
	ds_read_b128 v[60:63], v149 offset:16384
	ds_read_b128 v[100:103], v149 offset:17408
	ds_read_b128 v[104:107], v149 offset:18432
	ds_read_b128 v[108:111], v149 offset:19456
	ds_read_b128 v[112:115], v149 offset:20480
	ds_read_b128 v[116:119], v149 offset:21504
	ds_read_b128 v[120:123], v149 offset:22528
	ds_read_b128 v[124:127], v149 offset:23552
	global_load_lds_dwordx4 v[140:141], off
	v_lshl_add_u64 v[140:141], v[214:215], 0, s[38:39]
	s_mov_b32 m0, s49
	s_addc_u32 s97, s61, 0
	s_add_i32 s55, s89, s80
	global_load_lds_dwordx4 v[140:141], off
	v_lshl_add_u64 v[140:141], s[96:97], 0, v[130:131]
	s_mov_b32 m0, s55
	s_add_i32 s57, s55, 0x2000
	global_load_lds_dwordx4 v[140:141], off
	v_lshl_add_u64 v[140:141], s[96:97], 0, v[134:135]
	s_mov_b32 m0, s57
	v_lshl_add_u64 v[216:217], s[58:59], 0, v[128:129]
	global_load_lds_dwordx4 v[140:141], off
	v_lshl_add_u64 v[140:141], v[216:217], 0, s[38:39]
	s_mov_b32 m0, s81
	v_lshl_add_u64 v[218:219], s[58:59], 0, v[132:133]
	global_load_lds_dwordx4 v[140:141], off
	s_mov_b32 m0, s82
	v_lshl_add_u64 v[140:141], v[218:219], 0, s[38:39]
	global_load_lds_dwordx4 v[140:141], off
	s_waitcnt vmcnt(8) lgkmcnt(0)
	s_barrier
	v_mfma_f32_16x16x32_bf16 v[140:143], v[0:3], v[60:63], 0
	v_mfma_f32_16x16x32_bf16 v[156:159], v[0:3], v[104:107], 0
	v_mfma_f32_16x16x32_bf16 v[164:167], v[0:3], v[112:115], 0
	v_mfma_f32_16x16x32_bf16 v[0:3], v[0:3], v[120:123], 0
	v_mfma_f32_16x16x32_bf16 v[140:143], v[4:7], v[100:103], v[140:143]
	v_mfma_f32_16x16x32_bf16 v[156:159], v[4:7], v[108:111], v[156:159]
	v_mfma_f32_16x16x32_bf16 v[164:167], v[4:7], v[116:119], v[164:167]
	v_mfma_f32_16x16x32_bf16 v[0:3], v[4:7], v[124:127], v[0:3]
	v_mfma_f32_16x16x32_bf16 v[4:7], v[8:11], v[120:123], 0
	v_mfma_f32_16x16x32_bf16 v[152:155], v[8:11], v[60:63], 0
	v_mfma_f32_16x16x32_bf16 v[160:163], v[8:11], v[104:107], 0
	v_mfma_f32_16x16x32_bf16 v[168:171], v[8:11], v[112:115], 0
	v_mfma_f32_16x16x32_bf16 v[4:7], v[12:15], v[124:127], v[4:7]
	v_mfma_f32_16x16x32_bf16 v[152:155], v[12:15], v[100:103], v[152:155]
	v_mfma_f32_16x16x32_bf16 v[160:163], v[12:15], v[108:111], v[160:163]
	v_mfma_f32_16x16x32_bf16 v[168:171], v[12:15], v[116:119], v[168:171]
	v_mfma_f32_16x16x32_bf16 v[8:11], v[16:19], v[60:63], 0
	v_mfma_f32_16x16x32_bf16 v[12:15], v[24:27], v[60:63], 0
	v_mfma_f32_16x16x32_bf16 v[8:11], v[20:23], v[100:103], v[8:11]
	v_mfma_f32_16x16x32_bf16 v[12:15], v[28:31], v[100:103], v[12:15]
	v_mfma_f32_16x16x32_bf16 v[60:63], v[16:19], v[104:107], 0
	v_mfma_f32_16x16x32_bf16 v[100:103], v[24:27], v[104:107], 0
	v_mfma_f32_16x16x32_bf16 v[104:107], v[16:19], v[112:115], 0
	v_mfma_f32_16x16x32_bf16 v[16:19], v[16:19], v[120:123], 0
	v_mfma_f32_16x16x32_bf16 v[60:63], v[20:23], v[108:111], v[60:63]
	v_mfma_f32_16x16x32_bf16 v[100:103], v[28:31], v[108:111], v[100:103]
	v_mfma_f32_16x16x32_bf16 v[104:107], v[20:23], v[116:119], v[104:107]
	v_mfma_f32_16x16x32_bf16 v[108:111], v[24:27], v[112:115], 0
	v_mfma_f32_16x16x32_bf16 v[16:19], v[20:23], v[124:127], v[16:19]
	v_mfma_f32_16x16x32_bf16 v[20:23], v[24:27], v[120:123], 0
	v_mfma_f32_16x16x32_bf16 v[108:111], v[28:31], v[116:119], v[108:111]
	v_mfma_f32_16x16x32_bf16 v[20:23], v[28:31], v[124:127], v[20:23]
	s_barrier
	s_add_i32 s95, 0, 0x18000
	s_add_i32 vcc_lo, 0, 0x1c000
	v_add_u32_e32 v151, s95, v145
	v_add_u32_e32 v224, vcc_lo, v145
	ds_read_b128 v[24:27], v151
	ds_read_b128 v[28:31], v151 offset:1024
	ds_read_b128 v[112:115], v151 offset:2048
	ds_read_b128 v[116:119], v151 offset:3072
	ds_read_b128 v[120:123], v224
	ds_read_b128 v[124:127], v224 offset:1024
	ds_read_b128 v[172:175], v224 offset:2048
	ds_read_b128 v[176:179], v224 offset:3072
	s_add_u32 s96, s58, 0x10100
	s_addc_u32 s97, s59, 0
	s_mov_b32 m0, s83
	v_lshl_add_u64 v[220:221], s[96:97], 0, v[128:129]
	ds_read_b128 v[180:183], v149 offset:32768
	ds_read_b128 v[184:187], v149 offset:33792
	ds_read_b128 v[188:191], v149 offset:34816
	ds_read_b128 v[192:195], v149 offset:35840
	ds_read_b128 v[196:199], v149 offset:36864
	ds_read_b128 v[200:203], v149 offset:37888
	ds_read_b128 v[204:207], v149 offset:38912
	ds_read_b128 v[208:211], v149 offset:39936
	global_load_lds_dwordx4 v[220:221], off
	s_mov_b32 m0, s84
	v_lshl_add_u64 v[220:221], s[96:97], 0, v[132:133]
	global_load_lds_dwordx4 v[220:221], off
	s_waitcnt vmcnt(8) lgkmcnt(0)
	s_barrier
	v_mfma_f32_16x16x32_bf16 v[64:67], v[24:27], v[180:183], v[64:67]
	v_mfma_f32_16x16x32_bf16 v[68:71], v[112:115], v[180:183], v[68:71]
	v_mfma_f32_16x16x32_bf16 v[72:75], v[24:27], v[188:191], v[72:75]
	v_mfma_f32_16x16x32_bf16 v[76:79], v[112:115], v[188:191], v[76:79]
	v_mfma_f32_16x16x32_bf16 v[80:83], v[24:27], v[196:199], v[80:83]
	v_mfma_f32_16x16x32_bf16 v[84:87], v[112:115], v[196:199], v[84:87]
	v_mfma_f32_16x16x32_bf16 v[88:91], v[24:27], v[204:207], v[88:91]
	v_mfma_f32_16x16x32_bf16 v[92:95], v[112:115], v[204:207], v[92:95]
	v_mfma_f32_16x16x32_bf16 v[64:67], v[28:31], v[184:187], v[64:67]
	v_mfma_f32_16x16x32_bf16 v[68:71], v[116:119], v[184:187], v[68:71]
	v_mfma_f32_16x16x32_bf16 v[72:75], v[28:31], v[192:195], v[72:75]
	v_mfma_f32_16x16x32_bf16 v[76:79], v[116:119], v[192:195], v[76:79]
	v_mfma_f32_16x16x32_bf16 v[80:83], v[28:31], v[200:203], v[80:83]
	v_mfma_f32_16x16x32_bf16 v[84:87], v[116:119], v[200:203], v[84:87]
	v_mfma_f32_16x16x32_bf16 v[88:91], v[28:31], v[208:211], v[88:91]
	v_mfma_f32_16x16x32_bf16 v[92:95], v[116:119], v[208:211], v[92:95]
	v_mfma_f32_16x16x32_bf16 v[96:99], v[120:123], v[180:183], v[96:99]
	v_mfma_f32_16x16x32_bf16 v[32:35], v[172:175], v[180:183], v[32:35]
	v_mfma_f32_16x16x32_bf16 v[36:39], v[120:123], v[188:191], v[36:39]
	v_mfma_f32_16x16x32_bf16 v[40:43], v[172:175], v[188:191], v[40:43]
	v_mfma_f32_16x16x32_bf16 v[44:47], v[120:123], v[196:199], v[44:47]
	v_mfma_f32_16x16x32_bf16 v[48:51], v[172:175], v[196:199], v[48:51]
	v_mfma_f32_16x16x32_bf16 v[52:55], v[120:123], v[204:207], v[52:55]
	v_mfma_f32_16x16x32_bf16 v[56:59], v[172:175], v[204:207], v[56:59]
	v_mfma_f32_16x16x32_bf16 v[96:99], v[124:127], v[184:187], v[96:99]
	v_mfma_f32_16x16x32_bf16 v[32:35], v[176:179], v[184:187], v[32:35]
	v_mfma_f32_16x16x32_bf16 v[36:39], v[124:127], v[192:195], v[36:39]
	v_mfma_f32_16x16x32_bf16 v[40:43], v[176:179], v[192:195], v[40:43]
	v_mfma_f32_16x16x32_bf16 v[44:47], v[124:127], v[200:203], v[44:47]
	v_mfma_f32_16x16x32_bf16 v[48:51], v[176:179], v[200:203], v[48:51]
	v_mfma_f32_16x16x32_bf16 v[52:55], v[124:127], v[208:211], v[52:55]
	v_mfma_f32_16x16x32_bf16 v[56:59], v[176:179], v[208:211], v[56:59]
	s_barrier
	s_add_i32 s95, s95, s80
	s_add_i32 s93, s95, 0x2000
	v_lshl_add_u64 v[212:213], v[212:213], 0, s[40:41]
	s_mov_b32 m0, s95
	s_add_u32 s96, s60, 0x10180
	ds_read_b128 v[180:183], v149 offset:49152
	ds_read_b128 v[184:187], v149 offset:50176
	ds_read_b128 v[188:191], v149 offset:51200
	ds_read_b128 v[192:195], v149 offset:52224
	ds_read_b128 v[196:199], v149 offset:53248
	ds_read_b128 v[200:203], v149 offset:54272
	ds_read_b128 v[204:207], v149 offset:55296
	ds_read_b128 v[208:211], v149 offset:56320
	global_load_lds_dwordx4 v[212:213], off
	v_lshl_add_u64 v[212:213], v[214:215], 0, s[40:41]
	s_mov_b32 m0, s93
	s_addc_u32 s97, s61, 0
	s_add_i32 s60, vcc_lo, s80
	global_load_lds_dwordx4 v[212:213], off
	v_lshl_add_u64 v[212:213], s[96:97], 0, v[130:131]
	s_mov_b32 m0, s60
	s_add_i32 s61, s60, 0x2000
	global_load_lds_dwordx4 v[212:213], off
	s_mov_b32 m0, s61
	v_lshl_add_u64 v[212:213], s[96:97], 0, v[134:135]
	global_load_lds_dwordx4 v[212:213], off
	s_mov_b32 m0, s86
	v_lshl_add_u64 v[212:213], v[216:217], 0, s[40:41]
	global_load_lds_dwordx4 v[212:213], off
	s_mov_b32 m0, s87
	v_lshl_add_u64 v[212:213], v[218:219], 0, s[40:41]
	global_load_lds_dwordx4 v[212:213], off
	s_waitcnt vmcnt(8) lgkmcnt(0)
	s_barrier
	v_mfma_f32_16x16x32_bf16 v[0:3], v[24:27], v[204:207], v[0:3]
	v_mfma_f32_16x16x32_bf16 v[4:7], v[112:115], v[204:207], v[4:7]
	v_mfma_f32_16x16x32_bf16 v[140:143], v[24:27], v[180:183], v[140:143]
	v_mfma_f32_16x16x32_bf16 v[152:155], v[112:115], v[180:183], v[152:155]
	v_mfma_f32_16x16x32_bf16 v[156:159], v[24:27], v[188:191], v[156:159]
	v_mfma_f32_16x16x32_bf16 v[160:163], v[112:115], v[188:191], v[160:163]
	v_mfma_f32_16x16x32_bf16 v[164:167], v[24:27], v[196:199], v[164:167]
	v_mfma_f32_16x16x32_bf16 v[168:171], v[112:115], v[196:199], v[168:171]
	v_mfma_f32_16x16x32_bf16 v[0:3], v[28:31], v[208:211], v[0:3]
	v_mfma_f32_16x16x32_bf16 v[4:7], v[116:119], v[208:211], v[4:7]
	v_mfma_f32_16x16x32_bf16 v[140:143], v[28:31], v[184:187], v[140:143]
	v_mfma_f32_16x16x32_bf16 v[152:155], v[116:119], v[184:187], v[152:155]
	v_mfma_f32_16x16x32_bf16 v[156:159], v[28:31], v[192:195], v[156:159]
	v_mfma_f32_16x16x32_bf16 v[160:163], v[116:119], v[192:195], v[160:163]
	v_mfma_f32_16x16x32_bf16 v[164:167], v[28:31], v[200:203], v[164:167]
	v_mfma_f32_16x16x32_bf16 v[168:171], v[116:119], v[200:203], v[168:171]
	v_mfma_f32_16x16x32_bf16 v[8:11], v[120:123], v[180:183], v[8:11]
	v_mfma_f32_16x16x32_bf16 v[12:15], v[172:175], v[180:183], v[12:15]
	v_mfma_f32_16x16x32_bf16 v[24:27], v[120:123], v[188:191], v[60:63]
	v_mfma_f32_16x16x32_bf16 v[28:31], v[172:175], v[188:191], v[100:103]
	v_mfma_f32_16x16x32_bf16 v[60:63], v[120:123], v[196:199], v[104:107]
	v_mfma_f32_16x16x32_bf16 v[100:103], v[172:175], v[196:199], v[108:111]
	v_mfma_f32_16x16x32_bf16 v[16:19], v[120:123], v[204:207], v[16:19]
	v_mfma_f32_16x16x32_bf16 v[20:23], v[172:175], v[204:207], v[20:23]
	v_mfma_f32_16x16x32_bf16 v[8:11], v[124:127], v[184:187], v[8:11]
	v_mfma_f32_16x16x32_bf16 v[12:15], v[176:179], v[184:187], v[12:15]
	v_mfma_f32_16x16x32_bf16 v[24:27], v[124:127], v[192:195], v[24:27]
	v_mfma_f32_16x16x32_bf16 v[28:31], v[176:179], v[192:195], v[28:31]
	v_mfma_f32_16x16x32_bf16 v[60:63], v[124:127], v[200:203], v[60:63]
	v_mfma_f32_16x16x32_bf16 v[100:103], v[176:179], v[200:203], v[100:103]
	v_mfma_f32_16x16x32_bf16 v[16:19], v[124:127], v[208:211], v[16:19]
	v_mfma_f32_16x16x32_bf16 v[20:23], v[176:179], v[208:211], v[20:23]
	s_barrier
	ds_read_b128 v[104:107], v147
	ds_read_b128 v[108:111], v147 offset:1024
	ds_read_b128 v[112:115], v147 offset:2048
	ds_read_b128 v[116:119], v147 offset:3072
	ds_read_b128 v[120:123], v148
	ds_read_b128 v[124:127], v148 offset:1024
	ds_read_b128 v[172:175], v148 offset:2048
	ds_read_b128 v[176:179], v148 offset:3072
	s_add_u32 s58, s58, 0x10180
	s_addc_u32 s59, s59, 0
	s_mov_b32 m0, s94
	v_lshl_add_u64 v[212:213], s[58:59], 0, v[128:129]
	ds_read_b128 v[180:183], v149
	ds_read_b128 v[184:187], v149 offset:1024
	ds_read_b128 v[188:191], v149 offset:2048
	ds_read_b128 v[192:195], v149 offset:3072
	ds_read_b128 v[196:199], v149 offset:4096
	ds_read_b128 v[200:203], v149 offset:5120
	ds_read_b128 v[204:207], v149 offset:6144
	ds_read_b128 v[208:211], v149 offset:7168
	global_load_lds_dwordx4 v[212:213], off
	s_mov_b32 m0, s45
	v_lshl_add_u64 v[212:213], s[58:59], 0, v[132:133]
	global_load_lds_dwordx4 v[212:213], off
	s_waitcnt vmcnt(8) lgkmcnt(0)
	s_barrier
	v_mfma_f32_16x16x32_bf16 v[64:67], v[104:107], v[180:183], v[64:67]
	v_mfma_f32_16x16x32_bf16 v[68:71], v[112:115], v[180:183], v[68:71]
	v_mfma_f32_16x16x32_bf16 v[72:75], v[104:107], v[188:191], v[72:75]
	v_mfma_f32_16x16x32_bf16 v[76:79], v[112:115], v[188:191], v[76:79]
	v_mfma_f32_16x16x32_bf16 v[80:83], v[104:107], v[196:199], v[80:83]
	v_mfma_f32_16x16x32_bf16 v[84:87], v[112:115], v[196:199], v[84:87]
	v_mfma_f32_16x16x32_bf16 v[88:91], v[104:107], v[204:207], v[88:91]
	v_mfma_f32_16x16x32_bf16 v[64:67], v[108:111], v[184:187], v[64:67]
	v_mfma_f32_16x16x32_bf16 v[68:71], v[116:119], v[184:187], v[68:71]
	v_mfma_f32_16x16x32_bf16 v[72:75], v[108:111], v[192:195], v[72:75]
	v_mfma_f32_16x16x32_bf16 v[76:79], v[116:119], v[192:195], v[76:79]
	v_mfma_f32_16x16x32_bf16 v[80:83], v[108:111], v[200:203], v[80:83]
	v_mfma_f32_16x16x32_bf16 v[84:87], v[116:119], v[200:203], v[84:87]
	v_mfma_f32_16x16x32_bf16 v[212:215], v[108:111], v[208:211], v[88:91]
	v_mfma_f32_16x16x32_bf16 v[88:91], v[112:115], v[204:207], v[92:95]
	v_mfma_f32_16x16x32_bf16 v[216:219], v[116:119], v[208:211], v[88:91]
	v_mfma_f32_16x16x32_bf16 v[88:91], v[120:123], v[180:183], v[96:99]
	v_mfma_f32_16x16x32_bf16 v[32:35], v[172:175], v[180:183], v[32:35]
	v_mfma_f32_16x16x32_bf16 v[36:39], v[120:123], v[188:191], v[36:39]
	v_mfma_f32_16x16x32_bf16 v[40:43], v[172:175], v[188:191], v[40:43]
	v_mfma_f32_16x16x32_bf16 v[44:47], v[120:123], v[196:199], v[44:47]
	v_mfma_f32_16x16x32_bf16 v[48:51], v[172:175], v[196:199], v[48:51]
	v_mfma_f32_16x16x32_bf16 v[52:55], v[120:123], v[204:207], v[52:55]
	v_mfma_f32_16x16x32_bf16 v[56:59], v[172:175], v[204:207], v[56:59]
	v_mfma_f32_16x16x32_bf16 v[96:99], v[124:127], v[184:187], v[88:91]
	v_mfma_f32_16x16x32_bf16 v[32:35], v[176:179], v[184:187], v[32:35]
	v_mfma_f32_16x16x32_bf16 v[36:39], v[124:127], v[192:195], v[36:39]
	v_mfma_f32_16x16x32_bf16 v[40:43], v[176:179], v[192:195], v[40:43]
	v_mfma_f32_16x16x32_bf16 v[44:47], v[124:127], v[200:203], v[44:47]
	v_mfma_f32_16x16x32_bf16 v[48:51], v[176:179], v[200:203], v[48:51]
	v_mfma_f32_16x16x32_bf16 v[52:55], v[124:127], v[208:211], v[52:55]
	v_mfma_f32_16x16x32_bf16 v[56:59], v[176:179], v[208:211], v[56:59]
	s_barrier
	s_mov_b32 m0, s92
	v_lshl_add_u64 v[244:245], s[62:63], 0, v[130:131]
	s_add_u32 s58, s62, 0x10000
	ds_read_b128 v[88:91], v149 offset:16384
	ds_read_b128 v[92:95], v149 offset:17408
	ds_read_b128 v[180:183], v149 offset:18432
	ds_read_b128 v[184:187], v149 offset:19456
	ds_read_b128 v[188:191], v149 offset:20480
	ds_read_b128 v[192:195], v149 offset:21504
	ds_read_b128 v[196:199], v149 offset:22528
	ds_read_b128 v[200:203], v149 offset:23552
	global_load_lds_dwordx4 v[244:245], off
	v_lshl_add_u64 v[246:247], s[62:63], 0, v[134:135]
	s_mov_b32 m0, s49
	s_addc_u32 s59, s63, 0
	global_load_lds_dwordx4 v[246:247], off
	v_lshl_add_u64 v[204:205], s[58:59], 0, v[130:131]
	s_mov_b32 m0, s55
	v_lshl_add_u64 v[248:249], s[64:65], 0, v[128:129]
	global_load_lds_dwordx4 v[204:205], off
	v_lshl_add_u64 v[204:205], s[58:59], 0, v[134:135]
	s_mov_b32 m0, s57
	v_lshl_add_u64 v[250:251], s[64:65], 0, v[132:133]
	global_load_lds_dwordx4 v[204:205], off
	s_mov_b32 m0, s81
	s_nop 0
	global_load_lds_dwordx4 v[248:249], off
	s_mov_b32 m0, s82
	s_nop 0
	global_load_lds_dwordx4 v[250:251], off
	s_waitcnt vmcnt(8) lgkmcnt(0)
	s_barrier
	v_mfma_f32_16x16x32_bf16 v[0:3], v[104:107], v[196:199], v[0:3]
	v_mfma_f32_16x16x32_bf16 v[4:7], v[112:115], v[196:199], v[4:7]
	v_mfma_f32_16x16x32_bf16 v[140:143], v[104:107], v[88:91], v[140:143]
	v_mfma_f32_16x16x32_bf16 v[152:155], v[112:115], v[88:91], v[152:155]
	v_mfma_f32_16x16x32_bf16 v[156:159], v[104:107], v[180:183], v[156:159]
	v_mfma_f32_16x16x32_bf16 v[160:163], v[112:115], v[180:183], v[160:163]
	v_mfma_f32_16x16x32_bf16 v[164:167], v[104:107], v[188:191], v[164:167]
	v_mfma_f32_16x16x32_bf16 v[168:171], v[112:115], v[188:191], v[168:171]
	v_mfma_f32_16x16x32_bf16 v[0:3], v[108:111], v[200:203], v[0:3]
	v_mfma_f32_16x16x32_bf16 v[4:7], v[116:119], v[200:203], v[4:7]
	v_mfma_f32_16x16x32_bf16 v[140:143], v[108:111], v[92:95], v[140:143]
	v_mfma_f32_16x16x32_bf16 v[152:155], v[116:119], v[92:95], v[152:155]
	v_mfma_f32_16x16x32_bf16 v[156:159], v[108:111], v[184:187], v[156:159]
	v_mfma_f32_16x16x32_bf16 v[160:163], v[116:119], v[184:187], v[160:163]
	v_mfma_f32_16x16x32_bf16 v[164:167], v[108:111], v[192:195], v[164:167]
	v_mfma_f32_16x16x32_bf16 v[168:171], v[116:119], v[192:195], v[168:171]
	v_mfma_f32_16x16x32_bf16 v[8:11], v[120:123], v[88:91], v[8:11]
	v_mfma_f32_16x16x32_bf16 v[204:207], v[124:127], v[92:95], v[8:11]
	v_mfma_f32_16x16x32_bf16 v[8:11], v[172:175], v[88:91], v[12:15]
	v_mfma_f32_16x16x32_bf16 v[208:211], v[176:179], v[92:95], v[8:11]
	v_mfma_f32_16x16x32_bf16 v[8:11], v[120:123], v[180:183], v[24:27]
	v_mfma_f32_16x16x32_bf16 v[220:223], v[124:127], v[184:187], v[8:11]
	v_mfma_f32_16x16x32_bf16 v[8:11], v[172:175], v[180:183], v[28:31]
	v_mfma_f32_16x16x32_bf16 v[180:183], v[176:179], v[184:187], v[8:11]
	v_mfma_f32_16x16x32_bf16 v[8:11], v[120:123], v[188:191], v[60:63]
	v_mfma_f32_16x16x32_bf16 v[184:187], v[124:127], v[192:195], v[8:11]
	v_mfma_f32_16x16x32_bf16 v[8:11], v[172:175], v[188:191], v[100:103]
	v_mfma_f32_16x16x32_bf16 v[188:191], v[176:179], v[192:195], v[8:11]
	v_mfma_f32_16x16x32_bf16 v[8:11], v[120:123], v[196:199], v[16:19]
	v_mfma_f32_16x16x32_bf16 v[192:195], v[124:127], v[200:203], v[8:11]
	v_mfma_f32_16x16x32_bf16 v[8:11], v[172:175], v[196:199], v[20:23]
	v_mfma_f32_16x16x32_bf16 v[172:175], v[176:179], v[200:203], v[8:11]
	s_barrier
	s_nop 4
	ds_read_b128 v[8:11], v151
	ds_read_b128 v[12:15], v151 offset:1024
	ds_read_b128 v[16:19], v151 offset:2048
	ds_read_b128 v[20:23], v151 offset:3072
	ds_read_b128 v[176:179], v224
	ds_read_b128 v[196:199], v224 offset:1024
	ds_read_b128 v[200:203], v224 offset:2048
	ds_read_b128 v[224:227], v224 offset:3072
	s_add_u32 s58, s64, 0x10000
	s_addc_u32 s59, s65, 0
	s_mov_b32 m0, s83
	v_lshl_add_u64 v[88:89], s[58:59], 0, v[128:129]
	ds_read_b128 v[24:27], v149 offset:32768
	ds_read_b128 v[28:31], v149 offset:33792
	ds_read_b128 v[60:63], v149 offset:34816
	ds_read_b128 v[100:103], v149 offset:35840
	ds_read_b128 v[228:231], v149 offset:36864
	ds_read_b128 v[232:235], v149 offset:37888
	ds_read_b128 v[236:239], v149 offset:38912
	ds_read_b128 v[240:243], v149 offset:39936
	global_load_lds_dwordx4 v[88:89], off
	s_mov_b32 m0, s84
	v_lshl_add_u64 v[88:89], s[58:59], 0, v[132:133]
	global_load_lds_dwordx4 v[88:89], off
	s_waitcnt vmcnt(8) lgkmcnt(0)
	s_barrier
	v_mfma_f32_16x16x32_bf16 v[64:67], v[8:11], v[24:27], v[64:67]
	v_mfma_f32_16x16x32_bf16 v[120:123], v[12:15], v[28:31], v[64:67]
	v_mfma_f32_16x16x32_bf16 v[64:67], v[16:19], v[24:27], v[68:71]
	v_mfma_f32_16x16x32_bf16 v[124:127], v[20:23], v[28:31], v[64:67]
	v_mfma_f32_16x16x32_bf16 v[64:67], v[8:11], v[60:63], v[72:75]
	v_mfma_f32_16x16x32_bf16 v[104:107], v[12:15], v[100:103], v[64:67]
	v_mfma_f32_16x16x32_bf16 v[64:67], v[16:19], v[60:63], v[76:79]
	v_mfma_f32_16x16x32_bf16 v[108:111], v[20:23], v[100:103], v[64:67]
	v_mfma_f32_16x16x32_bf16 v[64:67], v[8:11], v[228:231], v[80:83]
	v_mfma_f32_16x16x32_bf16 v[88:91], v[12:15], v[232:235], v[64:67]
	v_mfma_f32_16x16x32_bf16 v[64:67], v[16:19], v[228:231], v[84:87]
	v_mfma_f32_16x16x32_bf16 v[92:95], v[20:23], v[232:235], v[64:67]
	v_mfma_f32_16x16x32_bf16 v[64:67], v[8:11], v[236:239], v[212:215]
	v_mfma_f32_16x16x32_bf16 v[72:75], v[12:15], v[240:243], v[64:67]
	v_mfma_f32_16x16x32_bf16 v[64:67], v[16:19], v[236:239], v[216:219]
	v_mfma_f32_16x16x32_bf16 v[76:79], v[20:23], v[240:243], v[64:67]
	v_mfma_f32_16x16x32_bf16 v[64:67], v[176:179], v[24:27], v[96:99]
	v_mfma_f32_16x16x32_bf16 v[24:27], v[200:203], v[24:27], v[32:35]
	v_mfma_f32_16x16x32_bf16 v[116:119], v[224:227], v[28:31], v[24:27]
	v_mfma_f32_16x16x32_bf16 v[24:27], v[176:179], v[60:63], v[36:39]
	v_mfma_f32_16x16x32_bf16 v[96:99], v[196:199], v[100:103], v[24:27]
	v_mfma_f32_16x16x32_bf16 v[24:27], v[200:203], v[60:63], v[40:43]
	v_mfma_f32_16x16x32_bf16 v[100:103], v[224:227], v[100:103], v[24:27]
	v_mfma_f32_16x16x32_bf16 v[24:27], v[176:179], v[228:231], v[44:47]
	v_mfma_f32_16x16x32_bf16 v[80:83], v[196:199], v[232:235], v[24:27]
	v_mfma_f32_16x16x32_bf16 v[24:27], v[200:203], v[228:231], v[48:51]
	v_mfma_f32_16x16x32_bf16 v[84:87], v[224:227], v[232:235], v[24:27]
	v_mfma_f32_16x16x32_bf16 v[24:27], v[176:179], v[236:239], v[52:55]
	v_mfma_f32_16x16x32_bf16 v[112:115], v[196:199], v[28:31], v[64:67]
	v_mfma_f32_16x16x32_bf16 v[64:67], v[196:199], v[240:243], v[24:27]
	v_mfma_f32_16x16x32_bf16 v[24:27], v[200:203], v[236:239], v[56:59]
	v_mfma_f32_16x16x32_bf16 v[68:71], v[224:227], v[240:243], v[24:27]
	s_barrier
	s_mov_b32 m0, s95
	s_nop 3
	v_lshl_add_u64 v[24:25], v[244:245], 0, s[18:19]
	s_add_u32 s58, s62, 0x10080
	ds_read_b128 v[32:35], v149 offset:49152
	ds_read_b128 v[36:39], v149 offset:50176
	ds_read_b128 v[212:215], v149 offset:51200
	ds_read_b128 v[216:219], v149 offset:52224
	ds_read_b128 v[228:231], v149 offset:53248
	ds_read_b128 v[232:235], v149 offset:54272
	ds_read_b128 v[236:239], v149 offset:55296
	ds_read_b128 v[240:243], v149 offset:56320
	global_load_lds_dwordx4 v[24:25], off
	v_lshl_add_u64 v[24:25], v[246:247], 0, s[18:19]
	s_mov_b32 m0, s93
	s_addc_u32 s59, s63, 0
	global_load_lds_dwordx4 v[24:25], off
	s_mov_b32 m0, s60
	v_lshl_add_u64 v[24:25], s[58:59], 0, v[130:131]
	global_load_lds_dwordx4 v[24:25], off
	s_mov_b32 m0, s61
	v_lshl_add_u64 v[24:25], s[58:59], 0, v[134:135]
	global_load_lds_dwordx4 v[24:25], off
	s_mov_b32 m0, s86
	v_lshl_add_u64 v[24:25], v[248:249], 0, s[18:19]
	global_load_lds_dwordx4 v[24:25], off
	s_mov_b32 m0, s87
	v_lshl_add_u64 v[24:25], v[250:251], 0, s[18:19]
	global_load_lds_dwordx4 v[24:25], off
	s_waitcnt vmcnt(8) lgkmcnt(0)
	s_barrier
	v_mfma_f32_16x16x32_bf16 v[24:27], v[8:11], v[32:35], v[140:143]
	v_mfma_f32_16x16x32_bf16 v[56:59], v[12:15], v[36:39], v[24:27]
	v_mfma_f32_16x16x32_bf16 v[24:27], v[16:19], v[32:35], v[152:155]
	v_mfma_f32_16x16x32_bf16 v[60:63], v[20:23], v[36:39], v[24:27]
	v_mfma_f32_16x16x32_bf16 v[24:27], v[8:11], v[212:215], v[156:159]
	v_mfma_f32_16x16x32_bf16 v[40:43], v[12:15], v[216:219], v[24:27]
	v_mfma_f32_16x16x32_bf16 v[24:27], v[16:19], v[212:215], v[160:163]
	v_mfma_f32_16x16x32_bf16 v[0:3], v[8:11], v[236:239], v[0:3]
	v_mfma_f32_16x16x32_bf16 v[44:47], v[20:23], v[216:219], v[24:27]
	v_mfma_f32_16x16x32_bf16 v[24:27], v[8:11], v[228:231], v[164:167]
	v_mfma_f32_16x16x32_bf16 v[28:31], v[16:19], v[228:231], v[168:171]
	v_mfma_f32_16x16x32_bf16 v[8:11], v[12:15], v[240:243], v[0:3]
	v_mfma_f32_16x16x32_bf16 v[0:3], v[16:19], v[236:239], v[4:7]
	v_mfma_f32_16x16x32_bf16 v[24:27], v[12:15], v[232:235], v[24:27]
	v_mfma_f32_16x16x32_bf16 v[28:31], v[20:23], v[232:235], v[28:31]
	v_mfma_f32_16x16x32_bf16 v[12:15], v[20:23], v[240:243], v[0:3]
	v_mfma_f32_16x16x32_bf16 v[0:3], v[176:179], v[32:35], v[204:207]
	v_mfma_f32_16x16x32_bf16 v[48:51], v[196:199], v[36:39], v[0:3]
	v_mfma_f32_16x16x32_bf16 v[0:3], v[200:203], v[32:35], v[208:211]
	v_mfma_f32_16x16x32_bf16 v[52:55], v[224:227], v[36:39], v[0:3]
	v_mfma_f32_16x16x32_bf16 v[0:3], v[176:179], v[212:215], v[220:223]
	v_mfma_f32_16x16x32_bf16 v[32:35], v[196:199], v[216:219], v[0:3]
	v_mfma_f32_16x16x32_bf16 v[0:3], v[200:203], v[212:215], v[180:183]
	v_mfma_f32_16x16x32_bf16 v[36:39], v[224:227], v[216:219], v[0:3]
	v_mfma_f32_16x16x32_bf16 v[0:3], v[176:179], v[228:231], v[184:187]
	v_mfma_f32_16x16x32_bf16 v[16:19], v[196:199], v[232:235], v[0:3]
	v_mfma_f32_16x16x32_bf16 v[0:3], v[200:203], v[228:231], v[188:191]
	v_mfma_f32_16x16x32_bf16 v[20:23], v[224:227], v[232:235], v[0:3]
	v_mfma_f32_16x16x32_bf16 v[0:3], v[176:179], v[236:239], v[192:195]
	v_mfma_f32_16x16x32_bf16 v[4:7], v[200:203], v[236:239], v[172:175]
	v_mfma_f32_16x16x32_bf16 v[0:3], v[196:199], v[240:243], v[0:3]
	v_mfma_f32_16x16x32_bf16 v[4:7], v[224:227], v[240:243], v[4:7]
	s_barrier
	s_andn2_b64 vcc, exec, s[24:25]
	s_cbranch_vccnz .LBB0_499
	s_barrier

.LBB0_546:
	v_add_u32_e32 v1, s80, v155
	ds_read_b128 v[146:149], v1
	ds_read_b128 v[150:153], v1 offset:1024
	ds_read_b128 v[162:165], v1 offset:2048
	ds_read_b128 v[166:169], v1 offset:3072
	v_add_u32_e32 v1, s81, v155
	ds_read_b128 v[170:173], v1
	ds_read_b128 v[174:177], v1 offset:1024
	ds_read_b128 v[178:181], v1 offset:2048
	ds_read_b128 v[182:185], v1 offset:3072
	s_and_b64 s[56:57], exec, s[56:57]
	s_cselect_b32 s57, s43, s91
	s_cselect_b32 s56, s89, s90
	s_add_u32 s96, s93, 0x40000
	s_addc_u32 s97, s94, 0
	v_lshl_add_u64 v[2:3], s[96:97], 0, v[132:133]
	s_add_i32 m0, s9, 0xc000
	ds_read_b128 v[186:189], v159
	ds_read_b128 v[190:193], v159 offset:1024
	ds_read_b128 v[194:197], v159 offset:2048
	ds_read_b128 v[198:201], v159 offset:3072
	ds_read_b128 v[202:205], v159 offset:4096
	ds_read_b128 v[206:209], v159 offset:5120
	ds_read_b128 v[210:213], v159 offset:6144
	ds_read_b128 v[214:217], v159 offset:7168
	global_load_lds_dwordx4 v[2:3], off
	s_add_i32 m0, s9, 0xe000
	v_lshl_add_u64 v[2:3], s[96:97], 0, v[136:137]
	global_load_lds_dwordx4 v[2:3], off
	s_waitcnt vmcnt(8) lgkmcnt(0)
	s_barrier
	v_mfma_f32_16x16x32_bf16 v[128:131], v[146:149], v[186:189], v[128:131]
	v_mfma_f32_16x16x32_bf16 v[124:127], v[162:165], v[186:189], v[124:127]
	v_mfma_f32_16x16x32_bf16 v[112:115], v[146:149], v[194:197], v[112:115]
	v_mfma_f32_16x16x32_bf16 v[108:111], v[162:165], v[194:197], v[108:111]
	v_mfma_f32_16x16x32_bf16 v[96:99], v[146:149], v[202:205], v[96:99]
	v_mfma_f32_16x16x32_bf16 v[92:95], v[162:165], v[202:205], v[92:95]
	v_mfma_f32_16x16x32_bf16 v[80:83], v[146:149], v[210:213], v[80:83]
	v_mfma_f32_16x16x32_bf16 v[76:79], v[162:165], v[210:213], v[76:79]
	v_mfma_f32_16x16x32_bf16 v[128:131], v[150:153], v[190:193], v[128:131]
	v_mfma_f32_16x16x32_bf16 v[124:127], v[166:169], v[190:193], v[124:127]
	v_mfma_f32_16x16x32_bf16 v[112:115], v[150:153], v[198:201], v[112:115]
	v_mfma_f32_16x16x32_bf16 v[108:111], v[166:169], v[198:201], v[108:111]
	v_mfma_f32_16x16x32_bf16 v[96:99], v[150:153], v[206:209], v[96:99]
	v_mfma_f32_16x16x32_bf16 v[92:95], v[166:169], v[206:209], v[92:95]
	v_mfma_f32_16x16x32_bf16 v[80:83], v[150:153], v[214:217], v[80:83]
	v_mfma_f32_16x16x32_bf16 v[76:79], v[166:169], v[214:217], v[76:79]
	v_mfma_f32_16x16x32_bf16 v[120:123], v[170:173], v[186:189], v[120:123]
	v_mfma_f32_16x16x32_bf16 v[116:119], v[178:181], v[186:189], v[116:119]
	v_mfma_f32_16x16x32_bf16 v[104:107], v[170:173], v[194:197], v[104:107]
	v_mfma_f32_16x16x32_bf16 v[100:103], v[178:181], v[194:197], v[100:103]
	v_mfma_f32_16x16x32_bf16 v[88:91], v[170:173], v[202:205], v[88:91]
	v_mfma_f32_16x16x32_bf16 v[84:87], v[178:181], v[202:205], v[84:87]
	v_mfma_f32_16x16x32_bf16 v[72:75], v[170:173], v[210:213], v[72:75]
	v_mfma_f32_16x16x32_bf16 v[68:71], v[178:181], v[210:213], v[68:71]
	v_mfma_f32_16x16x32_bf16 v[120:123], v[174:177], v[190:193], v[120:123]
	v_mfma_f32_16x16x32_bf16 v[116:119], v[182:185], v[190:193], v[116:119]
	v_mfma_f32_16x16x32_bf16 v[104:107], v[174:177], v[198:201], v[104:107]
	v_mfma_f32_16x16x32_bf16 v[100:103], v[182:185], v[198:201], v[100:103]
	v_mfma_f32_16x16x32_bf16 v[88:91], v[174:177], v[206:209], v[88:91]
	v_mfma_f32_16x16x32_bf16 v[84:87], v[182:185], v[206:209], v[84:87]
	v_mfma_f32_16x16x32_bf16 v[72:75], v[174:177], v[214:217], v[72:75]
	v_mfma_f32_16x16x32_bf16 v[68:71], v[182:185], v[214:217], v[68:71]
	s_barrier
	s_add_i32 s14, s80, s0
	v_lshl_add_u64 v[218:219], s[56:57], 0, v[134:135]
	s_mov_b32 m0, s14
	ds_read_b128 v[186:189], v159 offset:16384
	ds_read_b128 v[190:193], v159 offset:17408
	ds_read_b128 v[194:197], v159 offset:18432
	ds_read_b128 v[198:201], v159 offset:19456
	ds_read_b128 v[202:205], v159 offset:20480
	ds_read_b128 v[206:209], v159 offset:21504
	ds_read_b128 v[210:213], v159 offset:22528
	ds_read_b128 v[214:217], v159 offset:23552
	global_load_lds_dwordx4 v[218:219], off
	s_add_i32 m0, s14, 0x2000
	s_add_u32 s94, s56, 0x80000
	v_lshl_add_u64 v[220:221], s[56:57], 0, v[138:139]
	s_addc_u32 s95, s57, 0
	s_add_i32 s14, s81, s0
	global_load_lds_dwordx4 v[220:221], off
	v_lshl_add_u64 v[2:3], s[94:95], 0, v[134:135]
	s_mov_b32 m0, s14
	v_lshl_add_u64 v[222:223], s[58:59], 0, v[132:133]
	global_load_lds_dwordx4 v[2:3], off
	v_lshl_add_u64 v[2:3], s[94:95], 0, v[138:139]
	s_add_i32 m0, s14, 0x2000
	v_lshl_add_u64 v[224:225], s[58:59], 0, v[136:137]
	global_load_lds_dwordx4 v[2:3], off
	s_mov_b32 m0, s9
	s_nop 0
	global_load_lds_dwordx4 v[222:223], off
	s_mov_b32 m0, s62
	s_nop 0
	global_load_lds_dwordx4 v[224:225], off
	s_waitcnt vmcnt(8) lgkmcnt(0)
	s_barrier
	v_mfma_f32_16x16x32_bf16 v[64:67], v[146:149], v[186:189], v[64:67]
	v_mfma_f32_16x16x32_bf16 v[60:63], v[162:165], v[186:189], v[60:63]
	v_mfma_f32_16x16x32_bf16 v[48:51], v[146:149], v[194:197], v[48:51]
	v_mfma_f32_16x16x32_bf16 v[44:47], v[162:165], v[194:197], v[44:47]
	v_mfma_f32_16x16x32_bf16 v[32:35], v[146:149], v[202:205], v[32:35]
	v_mfma_f32_16x16x32_bf16 v[28:31], v[162:165], v[202:205], v[28:31]
	v_mfma_f32_16x16x32_bf16 v[16:19], v[146:149], v[210:213], v[16:19]
	v_mfma_f32_16x16x32_bf16 v[12:15], v[162:165], v[210:213], v[12:15]
	v_mfma_f32_16x16x32_bf16 v[64:67], v[150:153], v[190:193], v[64:67]
	v_mfma_f32_16x16x32_bf16 v[60:63], v[166:169], v[190:193], v[60:63]
	v_mfma_f32_16x16x32_bf16 v[48:51], v[150:153], v[198:201], v[48:51]
	v_mfma_f32_16x16x32_bf16 v[44:47], v[166:169], v[198:201], v[44:47]
	v_mfma_f32_16x16x32_bf16 v[32:35], v[150:153], v[206:209], v[32:35]
	v_mfma_f32_16x16x32_bf16 v[28:31], v[166:169], v[206:209], v[28:31]
	v_mfma_f32_16x16x32_bf16 v[16:19], v[150:153], v[214:217], v[16:19]
	v_mfma_f32_16x16x32_bf16 v[12:15], v[166:169], v[214:217], v[12:15]
	v_mfma_f32_16x16x32_bf16 v[56:59], v[170:173], v[186:189], v[56:59]
	v_mfma_f32_16x16x32_bf16 v[52:55], v[178:181], v[186:189], v[52:55]
	v_mfma_f32_16x16x32_bf16 v[40:43], v[170:173], v[194:197], v[40:43]
	v_mfma_f32_16x16x32_bf16 v[36:39], v[178:181], v[194:197], v[36:39]
	v_mfma_f32_16x16x32_bf16 v[24:27], v[170:173], v[202:205], v[24:27]
	v_mfma_f32_16x16x32_bf16 v[20:23], v[178:181], v[202:205], v[20:23]
	v_mfma_f32_16x16x32_bf16 v[8:11], v[170:173], v[210:213], v[8:11]
	v_mfma_f32_16x16x32_bf16 v[2:5], v[178:181], v[210:213], v[4:7]
	v_mfma_f32_16x16x32_bf16 v[56:59], v[174:177], v[190:193], v[56:59]
	v_mfma_f32_16x16x32_bf16 v[52:55], v[182:185], v[190:193], v[52:55]
	v_mfma_f32_16x16x32_bf16 v[40:43], v[174:177], v[198:201], v[40:43]
	v_mfma_f32_16x16x32_bf16 v[36:39], v[182:185], v[198:201], v[36:39]
	v_mfma_f32_16x16x32_bf16 v[24:27], v[174:177], v[206:209], v[24:27]
	v_mfma_f32_16x16x32_bf16 v[20:23], v[182:185], v[206:209], v[20:23]
	v_mfma_f32_16x16x32_bf16 v[8:11], v[174:177], v[214:217], v[8:11]
	v_mfma_f32_16x16x32_bf16 v[2:5], v[182:185], v[214:217], v[2:5]
	s_barrier
	s_add_i32 s14, 0, 0x18000
	v_add_u32_e32 v1, s14, v155
	s_add_i32 s93, 0, 0x1c000
	ds_read_b128 v[146:149], v1
	ds_read_b128 v[150:153], v1 offset:1024
	ds_read_b128 v[162:165], v1 offset:2048
	ds_read_b128 v[166:169], v1 offset:3072
	v_add_u32_e32 v1, s93, v155
	ds_read_b128 v[170:173], v1
	ds_read_b128 v[174:177], v1 offset:1024
	ds_read_b128 v[178:181], v1 offset:2048
	ds_read_b128 v[182:185], v1 offset:3072
	s_add_u32 s58, s58, 0x40000
	s_addc_u32 s59, s59, 0
	s_mov_b32 m0, s63
	v_lshl_add_u64 v[6:7], s[58:59], 0, v[132:133]
	ds_read_b128 v[186:189], v159 offset:32768
	ds_read_b128 v[190:193], v159 offset:33792
	ds_read_b128 v[194:197], v159 offset:34816
	ds_read_b128 v[198:201], v159 offset:35840
	ds_read_b128 v[202:205], v159 offset:36864
	ds_read_b128 v[206:209], v159 offset:37888
	ds_read_b128 v[210:213], v159 offset:38912
	ds_read_b128 v[214:217], v159 offset:39936
	global_load_lds_dwordx4 v[6:7], off
	s_mov_b32 m0, s64
	v_lshl_add_u64 v[6:7], s[58:59], 0, v[136:137]
	global_load_lds_dwordx4 v[6:7], off
	s_waitcnt vmcnt(8) lgkmcnt(0)
	s_barrier
	v_mfma_f32_16x16x32_bf16 v[128:131], v[146:149], v[186:189], v[128:131]
	v_mfma_f32_16x16x32_bf16 v[124:127], v[162:165], v[186:189], v[124:127]
	v_mfma_f32_16x16x32_bf16 v[112:115], v[146:149], v[194:197], v[112:115]
	v_mfma_f32_16x16x32_bf16 v[108:111], v[162:165], v[194:197], v[108:111]
	v_mfma_f32_16x16x32_bf16 v[96:99], v[146:149], v[202:205], v[96:99]
	v_mfma_f32_16x16x32_bf16 v[92:95], v[162:165], v[202:205], v[92:95]
	v_mfma_f32_16x16x32_bf16 v[80:83], v[146:149], v[210:213], v[80:83]
	v_mfma_f32_16x16x32_bf16 v[76:79], v[162:165], v[210:213], v[76:79]
	v_mfma_f32_16x16x32_bf16 v[128:131], v[150:153], v[190:193], v[128:131]
	v_mfma_f32_16x16x32_bf16 v[124:127], v[166:169], v[190:193], v[124:127]
	v_mfma_f32_16x16x32_bf16 v[112:115], v[150:153], v[198:201], v[112:115]
	v_mfma_f32_16x16x32_bf16 v[108:111], v[166:169], v[198:201], v[108:111]
	v_mfma_f32_16x16x32_bf16 v[96:99], v[150:153], v[206:209], v[96:99]
	v_mfma_f32_16x16x32_bf16 v[92:95], v[166:169], v[206:209], v[92:95]
	v_mfma_f32_16x16x32_bf16 v[80:83], v[150:153], v[214:217], v[80:83]
	v_mfma_f32_16x16x32_bf16 v[76:79], v[166:169], v[214:217], v[76:79]
	v_mfma_f32_16x16x32_bf16 v[120:123], v[170:173], v[186:189], v[120:123]
	v_mfma_f32_16x16x32_bf16 v[116:119], v[178:181], v[186:189], v[116:119]
	v_mfma_f32_16x16x32_bf16 v[104:107], v[170:173], v[194:197], v[104:107]
	v_mfma_f32_16x16x32_bf16 v[100:103], v[178:181], v[194:197], v[100:103]
	v_mfma_f32_16x16x32_bf16 v[88:91], v[170:173], v[202:205], v[88:91]
	v_mfma_f32_16x16x32_bf16 v[84:87], v[178:181], v[202:205], v[84:87]
	v_mfma_f32_16x16x32_bf16 v[72:75], v[170:173], v[210:213], v[72:75]
	v_mfma_f32_16x16x32_bf16 v[68:71], v[178:181], v[210:213], v[68:71]
	v_mfma_f32_16x16x32_bf16 v[120:123], v[174:177], v[190:193], v[120:123]
	v_mfma_f32_16x16x32_bf16 v[116:119], v[182:185], v[190:193], v[116:119]
	v_mfma_f32_16x16x32_bf16 v[104:107], v[174:177], v[198:201], v[104:107]
	v_mfma_f32_16x16x32_bf16 v[100:103], v[182:185], v[198:201], v[100:103]
	v_mfma_f32_16x16x32_bf16 v[88:91], v[174:177], v[206:209], v[88:91]
	v_mfma_f32_16x16x32_bf16 v[84:87], v[182:185], v[206:209], v[84:87]
	v_mfma_f32_16x16x32_bf16 v[72:75], v[174:177], v[214:217], v[72:75]
	v_mfma_f32_16x16x32_bf16 v[68:71], v[182:185], v[214:217], v[68:71]
	s_barrier
	s_add_i32 s14, s14, s0
	v_lshl_add_u64 v[6:7], v[218:219], 0, s[24:25]
	s_mov_b32 m0, s14
	ds_read_b128 v[186:189], v159 offset:49152
	ds_read_b128 v[190:193], v159 offset:50176
	ds_read_b128 v[194:197], v159 offset:51200
	ds_read_b128 v[198:201], v159 offset:52224
	ds_read_b128 v[202:205], v159 offset:53248
	ds_read_b128 v[206:209], v159 offset:54272
	ds_read_b128 v[210:213], v159 offset:55296
	ds_read_b128 v[214:217], v159 offset:56320
	global_load_lds_dwordx4 v[6:7], off
	s_add_i32 m0, s14, 0x2000
	s_add_u32 s56, s56, 0x80080
	v_lshl_add_u64 v[6:7], v[220:221], 0, s[24:25]
	s_addc_u32 s57, s57, 0
	s_add_i32 s14, s93, s0
	global_load_lds_dwordx4 v[6:7], off
	s_mov_b32 m0, s14
	v_lshl_add_u64 v[6:7], s[56:57], 0, v[134:135]
	global_load_lds_dwordx4 v[6:7], off
	s_add_i32 m0, s14, 0x2000
	v_lshl_add_u64 v[6:7], s[56:57], 0, v[138:139]
	global_load_lds_dwordx4 v[6:7], off
	s_mov_b32 m0, s72
	v_lshl_add_u64 v[6:7], v[222:223], 0, s[24:25]
	global_load_lds_dwordx4 v[6:7], off
	s_mov_b32 m0, s73
	v_lshl_add_u64 v[6:7], v[224:225], 0, s[24:25]
	global_load_lds_dwordx4 v[6:7], off
	s_waitcnt vmcnt(8) lgkmcnt(0)
	s_barrier
	v_mfma_f32_16x16x32_bf16 v[64:67], v[146:149], v[186:189], v[64:67]
	v_mfma_f32_16x16x32_bf16 v[60:63], v[162:165], v[186:189], v[60:63]
	v_mfma_f32_16x16x32_bf16 v[48:51], v[146:149], v[194:197], v[48:51]
	v_mfma_f32_16x16x32_bf16 v[44:47], v[162:165], v[194:197], v[44:47]
	v_mfma_f32_16x16x32_bf16 v[32:35], v[146:149], v[202:205], v[32:35]
	v_mfma_f32_16x16x32_bf16 v[28:31], v[162:165], v[202:205], v[28:31]
	v_mfma_f32_16x16x32_bf16 v[16:19], v[146:149], v[210:213], v[16:19]
	v_mfma_f32_16x16x32_bf16 v[12:15], v[162:165], v[210:213], v[12:15]
	v_mfma_f32_16x16x32_bf16 v[64:67], v[150:153], v[190:193], v[64:67]
	v_mfma_f32_16x16x32_bf16 v[60:63], v[166:169], v[190:193], v[60:63]
	v_mfma_f32_16x16x32_bf16 v[48:51], v[150:153], v[198:201], v[48:51]
	v_mfma_f32_16x16x32_bf16 v[44:47], v[166:169], v[198:201], v[44:47]
	v_mfma_f32_16x16x32_bf16 v[32:35], v[150:153], v[206:209], v[32:35]
	v_mfma_f32_16x16x32_bf16 v[28:31], v[166:169], v[206:209], v[28:31]
	v_mfma_f32_16x16x32_bf16 v[16:19], v[150:153], v[214:217], v[16:19]
	v_mfma_f32_16x16x32_bf16 v[12:15], v[166:169], v[214:217], v[12:15]
	v_mfma_f32_16x16x32_bf16 v[56:59], v[170:173], v[186:189], v[56:59]
	v_mfma_f32_16x16x32_bf16 v[52:55], v[178:181], v[186:189], v[52:55]
	v_mfma_f32_16x16x32_bf16 v[40:43], v[170:173], v[194:197], v[40:43]
	v_mfma_f32_16x16x32_bf16 v[36:39], v[178:181], v[194:197], v[36:39]
	v_mfma_f32_16x16x32_bf16 v[24:27], v[170:173], v[202:205], v[24:27]
	v_mfma_f32_16x16x32_bf16 v[20:23], v[178:181], v[202:205], v[20:23]
	v_mfma_f32_16x16x32_bf16 v[6:9], v[170:173], v[210:213], v[8:11]
	v_mfma_f32_16x16x32_bf16 v[2:5], v[178:181], v[210:213], v[2:5]
	v_mfma_f32_16x16x32_bf16 v[56:59], v[174:177], v[190:193], v[56:59]
	v_mfma_f32_16x16x32_bf16 v[52:55], v[182:185], v[190:193], v[52:55]
	v_mfma_f32_16x16x32_bf16 v[40:43], v[174:177], v[198:201], v[40:43]
	v_mfma_f32_16x16x32_bf16 v[36:39], v[182:185], v[198:201], v[36:39]
	v_mfma_f32_16x16x32_bf16 v[24:27], v[174:177], v[206:209], v[24:27]
	v_mfma_f32_16x16x32_bf16 v[20:23], v[182:185], v[206:209], v[20:23]
	v_mfma_f32_16x16x32_bf16 v[8:11], v[174:177], v[214:217], v[6:9]
	v_mfma_f32_16x16x32_bf16 v[4:7], v[182:185], v[214:217], v[2:5]
	s_barrier
	s_add_i32 s14, s92, 2
	s_add_u32 s54, s54, 0x100
	s_addc_u32 s55, s55, 0
	s_add_u32 s90, s90, 0x100
	s_addc_u32 s91, s91, 0
	s_cmp_gt_u32 s92, 29
	s_mov_b32 s92, s14
	s_cbranch_scc1 .LBB0_554

.LBB0_658:
	v_add_u32_e32 v1, s61, v201
	ds_read_b128 v[102:105], v1
	ds_read_b128 v[106:109], v1 offset:1024
	ds_read_b128 v[110:113], v1 offset:2048
	ds_read_b128 v[114:117], v1 offset:3072
	v_add_u32_e32 v1, s62, v201
	ds_read_b128 v[118:121], v1
	ds_read_b128 v[156:159], v1 offset:1024
	ds_read_b128 v[160:163], v1 offset:2048
	ds_read_b128 v[164:167], v1 offset:3072
	s_and_b64 s[48:49], exec, s[48:49]
	s_cselect_b32 s49, s27, s78
	s_cselect_b32 s48, s29, s73
	s_add_u32 s80, s80, 0x40000
	s_addc_u32 s81, s81, 0
	v_lshl_add_u64 v[2:3], s[80:81], 0, v[178:179]
	s_add_i32 m0, s41, 0xc000
	ds_read_b128 v[168:171], v207
	ds_read_b128 v[184:187], v207 offset:1024
	ds_read_b128 v[188:191], v207 offset:2048
	ds_read_b128 v[192:195], v207 offset:3072
	ds_read_b128 v[208:211], v207 offset:4096
	ds_read_b128 v[212:215], v207 offset:5120
	ds_read_b128 v[216:219], v207 offset:6144
	ds_read_b128 v[220:223], v207 offset:7168
	global_load_lds_dwordx4 v[2:3], off
	s_add_i32 m0, s41, 0xe000
	v_lshl_add_u64 v[2:3], s[80:81], 0, v[174:175]
	global_load_lds_dwordx4 v[2:3], off
	s_waitcnt vmcnt(8) lgkmcnt(0)
	s_barrier
	v_mfma_f32_16x16x32_bf16 v[152:155], v[102:105], v[168:171], v[152:155]
	v_mfma_f32_16x16x32_bf16 v[148:151], v[110:113], v[168:171], v[148:151]
	v_mfma_f32_16x16x32_bf16 v[144:147], v[102:105], v[188:191], v[144:147]
	v_mfma_f32_16x16x32_bf16 v[140:143], v[110:113], v[188:191], v[140:143]
	v_mfma_f32_16x16x32_bf16 v[136:139], v[102:105], v[208:211], v[136:139]
	v_mfma_f32_16x16x32_bf16 v[132:135], v[110:113], v[208:211], v[132:135]
	v_mfma_f32_16x16x32_bf16 v[128:131], v[102:105], v[216:219], v[128:131]
	v_mfma_f32_16x16x32_bf16 v[122:125], v[110:113], v[216:219], v[124:127]
	v_mfma_f32_16x16x32_bf16 v[152:155], v[106:109], v[184:187], v[152:155]
	v_mfma_f32_16x16x32_bf16 v[148:151], v[114:117], v[184:187], v[148:151]
	v_mfma_f32_16x16x32_bf16 v[144:147], v[106:109], v[192:195], v[144:147]
	v_mfma_f32_16x16x32_bf16 v[140:143], v[114:117], v[192:195], v[140:143]
	v_mfma_f32_16x16x32_bf16 v[136:139], v[106:109], v[212:215], v[136:139]
	v_mfma_f32_16x16x32_bf16 v[132:135], v[114:117], v[212:215], v[132:135]
	v_mfma_f32_16x16x32_bf16 v[128:131], v[106:109], v[220:223], v[128:131]
	v_mfma_f32_16x16x32_bf16 v[122:125], v[114:117], v[220:223], v[122:125]
	v_mfma_f32_16x16x32_bf16 v[64:67], v[118:121], v[168:171], v[64:67]
	v_mfma_f32_16x16x32_bf16 v[60:63], v[160:163], v[168:171], v[60:63]
	v_mfma_f32_16x16x32_bf16 v[56:59], v[118:121], v[188:191], v[56:59]
	v_mfma_f32_16x16x32_bf16 v[52:55], v[160:163], v[188:191], v[52:55]
	v_mfma_f32_16x16x32_bf16 v[48:51], v[118:121], v[208:211], v[48:51]
	v_mfma_f32_16x16x32_bf16 v[44:47], v[160:163], v[208:211], v[44:47]
	v_mfma_f32_16x16x32_bf16 v[40:43], v[118:121], v[216:219], v[40:43]
	v_mfma_f32_16x16x32_bf16 v[36:39], v[160:163], v[216:219], v[36:39]
	v_mfma_f32_16x16x32_bf16 v[64:67], v[156:159], v[184:187], v[64:67]
	v_mfma_f32_16x16x32_bf16 v[60:63], v[164:167], v[184:187], v[60:63]
	v_mfma_f32_16x16x32_bf16 v[56:59], v[156:159], v[192:195], v[56:59]
	v_mfma_f32_16x16x32_bf16 v[52:55], v[164:167], v[192:195], v[52:55]
	v_mfma_f32_16x16x32_bf16 v[48:51], v[156:159], v[212:215], v[48:51]
	v_mfma_f32_16x16x32_bf16 v[44:47], v[164:167], v[212:215], v[44:47]
	v_mfma_f32_16x16x32_bf16 v[40:43], v[156:159], v[220:223], v[40:43]
	v_mfma_f32_16x16x32_bf16 v[36:39], v[164:167], v[220:223], v[36:39]
	s_barrier
	s_add_i32 s6, s61, s53
	v_lshl_add_u64 v[196:197], s[48:49], 0, v[176:177]
	s_mov_b32 m0, s6
	ds_read_b128 v[168:171], v207 offset:16384
	ds_read_b128 v[184:187], v207 offset:17408
	ds_read_b128 v[188:191], v207 offset:18432
	ds_read_b128 v[192:195], v207 offset:19456
	ds_read_b128 v[208:211], v207 offset:20480
	ds_read_b128 v[212:215], v207 offset:21504
	ds_read_b128 v[216:219], v207 offset:22528
	ds_read_b128 v[220:223], v207 offset:23552
	global_load_lds_dwordx4 v[196:197], off
	s_add_i32 m0, s6, 0x2000
	s_add_u32 s80, s48, 0x80000
	v_lshl_add_u64 v[224:225], s[48:49], 0, v[172:173]
	s_addc_u32 s81, s49, 0
	s_add_i32 s6, s62, s53
	global_load_lds_dwordx4 v[224:225], off
	v_lshl_add_u64 v[2:3], s[80:81], 0, v[176:177]
	s_mov_b32 m0, s6
	v_lshl_add_u64 v[226:227], s[50:51], 0, v[178:179]
	global_load_lds_dwordx4 v[2:3], off
	v_lshl_add_u64 v[2:3], s[80:81], 0, v[172:173]
	s_add_i32 m0, s6, 0x2000
	v_lshl_add_u64 v[228:229], s[50:51], 0, v[174:175]
	global_load_lds_dwordx4 v[2:3], off
	s_mov_b32 m0, s41
	s_nop 0
	global_load_lds_dwordx4 v[226:227], off
	s_mov_b32 m0, s56
	s_nop 0
	global_load_lds_dwordx4 v[228:229], off
	s_waitcnt vmcnt(8) lgkmcnt(0)
	s_barrier
	v_mfma_f32_16x16x32_bf16 v[96:99], v[102:105], v[168:171], v[96:99]
	v_mfma_f32_16x16x32_bf16 v[92:95], v[110:113], v[168:171], v[92:95]
	v_mfma_f32_16x16x32_bf16 v[88:91], v[102:105], v[188:191], v[88:91]
	v_mfma_f32_16x16x32_bf16 v[84:87], v[110:113], v[188:191], v[84:87]
	v_mfma_f32_16x16x32_bf16 v[80:83], v[102:105], v[208:211], v[80:83]
	v_mfma_f32_16x16x32_bf16 v[76:79], v[110:113], v[208:211], v[76:79]
	v_mfma_f32_16x16x32_bf16 v[72:75], v[102:105], v[216:219], v[72:75]
	v_mfma_f32_16x16x32_bf16 v[68:71], v[110:113], v[216:219], v[68:71]
	v_mfma_f32_16x16x32_bf16 v[96:99], v[106:109], v[184:187], v[96:99]
	v_mfma_f32_16x16x32_bf16 v[92:95], v[114:117], v[184:187], v[92:95]
	v_mfma_f32_16x16x32_bf16 v[88:91], v[106:109], v[192:195], v[88:91]
	v_mfma_f32_16x16x32_bf16 v[84:87], v[114:117], v[192:195], v[84:87]
	v_mfma_f32_16x16x32_bf16 v[80:83], v[106:109], v[212:215], v[80:83]
	v_mfma_f32_16x16x32_bf16 v[76:79], v[114:117], v[212:215], v[76:79]
	v_mfma_f32_16x16x32_bf16 v[72:75], v[106:109], v[220:223], v[72:75]
	v_mfma_f32_16x16x32_bf16 v[68:71], v[114:117], v[220:223], v[68:71]
	v_mfma_f32_16x16x32_bf16 v[32:35], v[118:121], v[168:171], v[32:35]
	v_mfma_f32_16x16x32_bf16 v[28:31], v[160:163], v[168:171], v[28:31]
	v_mfma_f32_16x16x32_bf16 v[24:27], v[118:121], v[188:191], v[24:27]
	v_mfma_f32_16x16x32_bf16 v[20:23], v[160:163], v[188:191], v[20:23]
	v_mfma_f32_16x16x32_bf16 v[16:19], v[118:121], v[208:211], v[16:19]
	v_mfma_f32_16x16x32_bf16 v[12:15], v[160:163], v[208:211], v[12:15]
	v_mfma_f32_16x16x32_bf16 v[8:11], v[118:121], v[216:219], v[8:11]
	v_mfma_f32_16x16x32_bf16 v[2:5], v[160:163], v[216:219], v[4:7]
	v_mfma_f32_16x16x32_bf16 v[32:35], v[156:159], v[184:187], v[32:35]
	v_mfma_f32_16x16x32_bf16 v[28:31], v[164:167], v[184:187], v[28:31]
	v_mfma_f32_16x16x32_bf16 v[24:27], v[156:159], v[192:195], v[24:27]
	v_mfma_f32_16x16x32_bf16 v[20:23], v[164:167], v[192:195], v[20:23]
	v_mfma_f32_16x16x32_bf16 v[16:19], v[156:159], v[212:215], v[16:19]
	v_mfma_f32_16x16x32_bf16 v[12:15], v[164:167], v[212:215], v[12:15]
	v_mfma_f32_16x16x32_bf16 v[8:11], v[156:159], v[220:223], v[8:11]
	v_mfma_f32_16x16x32_bf16 v[2:5], v[164:167], v[220:223], v[2:5]
	s_barrier
	s_add_i32 s6, 0, 0x18000
	v_add_u32_e32 v1, s6, v201
	s_add_i32 s80, 0, 0x1c000
	ds_read_b128 v[102:105], v1
	ds_read_b128 v[106:109], v1 offset:1024
	ds_read_b128 v[110:113], v1 offset:2048
	ds_read_b128 v[114:117], v1 offset:3072
	v_add_u32_e32 v1, s80, v201
	ds_read_b128 v[118:121], v1
	ds_read_b128 v[156:159], v1 offset:1024
	ds_read_b128 v[160:163], v1 offset:2048
	ds_read_b128 v[164:167], v1 offset:3072
	s_add_u32 s50, s50, 0x40000
	s_addc_u32 s51, s51, 0
	s_mov_b32 m0, s57
	v_lshl_add_u64 v[6:7], s[50:51], 0, v[178:179]
	ds_read_b128 v[168:171], v207 offset:32768
	ds_read_b128 v[184:187], v207 offset:33792
	ds_read_b128 v[188:191], v207 offset:34816
	ds_read_b128 v[192:195], v207 offset:35840
	ds_read_b128 v[208:211], v207 offset:36864
	ds_read_b128 v[212:215], v207 offset:37888
	ds_read_b128 v[216:219], v207 offset:38912
	ds_read_b128 v[220:223], v207 offset:39936
	global_load_lds_dwordx4 v[6:7], off
	s_mov_b32 m0, s58
	v_lshl_add_u64 v[6:7], s[50:51], 0, v[174:175]
	global_load_lds_dwordx4 v[6:7], off
	s_waitcnt vmcnt(8) lgkmcnt(0)
	s_barrier
	v_mfma_f32_16x16x32_bf16 v[152:155], v[102:105], v[168:171], v[152:155]
	v_mfma_f32_16x16x32_bf16 v[148:151], v[110:113], v[168:171], v[148:151]
	v_mfma_f32_16x16x32_bf16 v[144:147], v[102:105], v[188:191], v[144:147]
	v_mfma_f32_16x16x32_bf16 v[140:143], v[110:113], v[188:191], v[140:143]
	v_mfma_f32_16x16x32_bf16 v[136:139], v[102:105], v[208:211], v[136:139]
	v_mfma_f32_16x16x32_bf16 v[132:135], v[110:113], v[208:211], v[132:135]
	v_mfma_f32_16x16x32_bf16 v[126:129], v[102:105], v[216:219], v[128:131]
	v_mfma_f32_16x16x32_bf16 v[122:125], v[110:113], v[216:219], v[122:125]
	v_mfma_f32_16x16x32_bf16 v[152:155], v[106:109], v[184:187], v[152:155]
	v_mfma_f32_16x16x32_bf16 v[148:151], v[114:117], v[184:187], v[148:151]
	v_mfma_f32_16x16x32_bf16 v[144:147], v[106:109], v[192:195], v[144:147]
	v_mfma_f32_16x16x32_bf16 v[140:143], v[114:117], v[192:195], v[140:143]
	v_mfma_f32_16x16x32_bf16 v[136:139], v[106:109], v[212:215], v[136:139]
	v_mfma_f32_16x16x32_bf16 v[132:135], v[114:117], v[212:215], v[132:135]
	v_mfma_f32_16x16x32_bf16 v[128:131], v[106:109], v[220:223], v[126:129]
	v_mfma_f32_16x16x32_bf16 v[124:127], v[114:117], v[220:223], v[122:125]
	v_mfma_f32_16x16x32_bf16 v[64:67], v[118:121], v[168:171], v[64:67]
	v_mfma_f32_16x16x32_bf16 v[60:63], v[160:163], v[168:171], v[60:63]
	v_mfma_f32_16x16x32_bf16 v[56:59], v[118:121], v[188:191], v[56:59]
	v_mfma_f32_16x16x32_bf16 v[52:55], v[160:163], v[188:191], v[52:55]
	v_mfma_f32_16x16x32_bf16 v[48:51], v[118:121], v[208:211], v[48:51]
	v_mfma_f32_16x16x32_bf16 v[44:47], v[160:163], v[208:211], v[44:47]
	v_mfma_f32_16x16x32_bf16 v[40:43], v[118:121], v[216:219], v[40:43]
	v_mfma_f32_16x16x32_bf16 v[36:39], v[160:163], v[216:219], v[36:39]
	v_mfma_f32_16x16x32_bf16 v[64:67], v[156:159], v[184:187], v[64:67]
	v_mfma_f32_16x16x32_bf16 v[60:63], v[164:167], v[184:187], v[60:63]
	v_mfma_f32_16x16x32_bf16 v[56:59], v[156:159], v[192:195], v[56:59]
	v_mfma_f32_16x16x32_bf16 v[52:55], v[164:167], v[192:195], v[52:55]
	v_mfma_f32_16x16x32_bf16 v[48:51], v[156:159], v[212:215], v[48:51]
	v_mfma_f32_16x16x32_bf16 v[44:47], v[164:167], v[212:215], v[44:47]
	v_mfma_f32_16x16x32_bf16 v[40:43], v[156:159], v[220:223], v[40:43]
	v_mfma_f32_16x16x32_bf16 v[36:39], v[164:167], v[220:223], v[36:39]
	s_barrier
	s_add_i32 s6, s6, s53
	v_lshl_add_u64 v[6:7], v[196:197], 0, s[14:15]
	s_mov_b32 m0, s6
	ds_read_b128 v[168:171], v207 offset:49152
	ds_read_b128 v[184:187], v207 offset:50176
	ds_read_b128 v[188:191], v207 offset:51200
	ds_read_b128 v[192:195], v207 offset:52224
	ds_read_b128 v[208:211], v207 offset:53248
	ds_read_b128 v[212:215], v207 offset:54272
	ds_read_b128 v[216:219], v207 offset:55296
	ds_read_b128 v[220:223], v207 offset:56320
	global_load_lds_dwordx4 v[6:7], off
	s_add_i32 m0, s6, 0x2000
	s_add_u32 s48, s48, 0x80080
	v_lshl_add_u64 v[6:7], v[224:225], 0, s[14:15]
	s_addc_u32 s49, s49, 0
	s_add_i32 s6, s80, s53
	global_load_lds_dwordx4 v[6:7], off
	s_mov_b32 m0, s6
	v_lshl_add_u64 v[6:7], s[48:49], 0, v[176:177]
	global_load_lds_dwordx4 v[6:7], off
	s_add_i32 m0, s6, 0x2000
	v_lshl_add_u64 v[6:7], s[48:49], 0, v[172:173]
	global_load_lds_dwordx4 v[6:7], off
	s_mov_b32 m0, s59
	v_lshl_add_u64 v[6:7], v[226:227], 0, s[14:15]
	global_load_lds_dwordx4 v[6:7], off
	s_mov_b32 m0, s60
	v_lshl_add_u64 v[6:7], v[228:229], 0, s[14:15]
	global_load_lds_dwordx4 v[6:7], off
	s_waitcnt vmcnt(8) lgkmcnt(0)
	s_barrier
	v_mfma_f32_16x16x32_bf16 v[96:99], v[102:105], v[168:171], v[96:99]
	v_mfma_f32_16x16x32_bf16 v[92:95], v[110:113], v[168:171], v[92:95]
	v_mfma_f32_16x16x32_bf16 v[88:91], v[102:105], v[188:191], v[88:91]
	v_mfma_f32_16x16x32_bf16 v[84:87], v[110:113], v[188:191], v[84:87]
	v_mfma_f32_16x16x32_bf16 v[80:83], v[102:105], v[208:211], v[80:83]
	v_mfma_f32_16x16x32_bf16 v[76:79], v[110:113], v[208:211], v[76:79]
	v_mfma_f32_16x16x32_bf16 v[72:75], v[102:105], v[216:219], v[72:75]
	v_mfma_f32_16x16x32_bf16 v[68:71], v[110:113], v[216:219], v[68:71]
	v_mfma_f32_16x16x32_bf16 v[96:99], v[106:109], v[184:187], v[96:99]
	v_mfma_f32_16x16x32_bf16 v[92:95], v[114:117], v[184:187], v[92:95]
	v_mfma_f32_16x16x32_bf16 v[88:91], v[106:109], v[192:195], v[88:91]
	v_mfma_f32_16x16x32_bf16 v[84:87], v[114:117], v[192:195], v[84:87]
	v_mfma_f32_16x16x32_bf16 v[80:83], v[106:109], v[212:215], v[80:83]
	v_mfma_f32_16x16x32_bf16 v[76:79], v[114:117], v[212:215], v[76:79]
	v_mfma_f32_16x16x32_bf16 v[72:75], v[106:109], v[220:223], v[72:75]
	v_mfma_f32_16x16x32_bf16 v[68:71], v[114:117], v[220:223], v[68:71]
	v_mfma_f32_16x16x32_bf16 v[32:35], v[118:121], v[168:171], v[32:35]
	v_mfma_f32_16x16x32_bf16 v[28:31], v[160:163], v[168:171], v[28:31]
	v_mfma_f32_16x16x32_bf16 v[24:27], v[118:121], v[188:191], v[24:27]
	v_mfma_f32_16x16x32_bf16 v[20:23], v[160:163], v[188:191], v[20:23]
	v_mfma_f32_16x16x32_bf16 v[16:19], v[118:121], v[208:211], v[16:19]
	v_mfma_f32_16x16x32_bf16 v[12:15], v[160:163], v[208:211], v[12:15]
	v_mfma_f32_16x16x32_bf16 v[6:9], v[118:121], v[216:219], v[8:11]
	v_mfma_f32_16x16x32_bf16 v[2:5], v[160:163], v[216:219], v[2:5]
	v_mfma_f32_16x16x32_bf16 v[32:35], v[156:159], v[184:187], v[32:35]
	v_mfma_f32_16x16x32_bf16 v[28:31], v[164:167], v[184:187], v[28:31]
	v_mfma_f32_16x16x32_bf16 v[24:27], v[156:159], v[192:195], v[24:27]
	v_mfma_f32_16x16x32_bf16 v[20:23], v[164:167], v[192:195], v[20:23]
	v_mfma_f32_16x16x32_bf16 v[16:19], v[156:159], v[212:215], v[16:19]
	v_mfma_f32_16x16x32_bf16 v[12:15], v[164:167], v[212:215], v[12:15]
	v_mfma_f32_16x16x32_bf16 v[8:11], v[156:159], v[220:223], v[6:9]
	v_mfma_f32_16x16x32_bf16 v[4:7], v[164:167], v[220:223], v[2:5]
	s_barrier
	s_add_i32 s6, s79, 2
	s_add_u32 s44, s44, 0x100
	s_addc_u32 s45, s45, 0
	s_add_u32 s73, s73, 0x100
	s_addc_u32 s78, s78, 0
	s_cmp_gt_u32 s79, 29
	s_cbranch_scc1 .LBB0_660
	s_mov_b32 s79, s6
	s_cmp_lg_u32 s79, 16
	s_cbranch_scc0 .LBB0_652
	s_branch .LBB0_653
